# combo3 = combo2 + non-temporal hint on the read-once f32 weight and x loads of the conversion prologue
# baseline (speedup 1.0000x reference)
; #define LAS __attribute__((address_space(3)))
; __device__ __forceinline__ void tr_item(const float* W, int K, int N, bf16_t* WT, const float* gain, int perm, LAS float* scr, int item, int lane) {
;     const int nblk = N / 64, kb = item / nblk, nb = item % nblk, k0 = 64 * kb, n0 = 64 * nb, lr = lane >> 4, c4 = lane & 15;
;     f32x4 v[16];
; #pragma unroll
;     for (int i = 0; i < 16; ++i) v[i] = *(const f32x4*)(W + (size_t)(k0 + lr + 4 * i) * N + n0 + 4 * c4);
;     if (gain) {
; #pragma unroll
;         for (int i = 0; i < 16; ++i) v[i] = v[i] * gain[k0 + lr + 4 * i];
;     }
; #pragma unroll
;     for (int i = 0; i < 16; ++i)
; #pragma unroll
;         for (int e = 0; e < 4; ++e) scr[(lr + 4 * i) * 65 + 4 * c4 + e] = v[i][e];
;     asm volatile("s_waitcnt lgkmcnt(0)" ::: "memory");
; __global__ void __launch_bounds__(512, 2) mk_fwd(Args a) {
;     ...
;                 tr_item((const float*)a.in[15] + (size_t)l * DM * DM, DM, DM, (bf16_t*)((unsigned char*)wl + WT_OUT), nullptr, 0, scr, r, lane);
.LBB0_607:
	s_cmpk_gt_i32 s14, 0x4fff
	s_cselect_b64 s[0:1], -1, 0
	s_and_b64 s[6:7], s[0:1], exec
	s_cselect_b32 s8, 0xffffb000, 0
	s_cselect_b32 s6, 0xa000000, 0
	s_add_i32 s8, s8, s14
	s_add_u32 s15, s60, s6
	s_addc_u32 s34, s61, 0
	s_cmpk_gt_i32 s8, 0x15ff
	s_mov_b64 s[6:7], -1
	s_cbranch_scc0 .LBB0_629
	s_cmpk_gt_u32 s8, 0x2bff
	s_cbranch_scc0 .LBB0_624
	s_cmpk_gt_u32 s8, 0x36ff
	s_cbranch_scc0 .LBB0_621
	s_cmpk_gt_u32 s8, 0x41ff
	s_cbranch_scc0 .LBB0_618
	s_cmpk_gt_u32 s8, 0x4bff
	s_cbranch_scc0 .LBB0_613
	s_and_b64 s[6:7], s[0:1], exec
	s_cselect_b32 s6, 0x1000000, 0
	s_add_u32 s7, s50, s6
	s_addc_u32 s9, s51, 0
	s_lshl_b32 s6, s8, 1
	s_andn2_b32 s6, s6, 63
	s_add_i32 s74, s6, 0xffff6800
	s_and_b32 s6, s12, 0x7c0
	s_lshl_b32 s17, s6, 2
	s_add_u32 s18, s7, s17
	v_or_b32_e32 v60, s74, v70
	s_addc_u32 s19, s9, 0
	v_lshlrev_b32_e32 v128, 2, v64
	v_mov_b32_e32 v61, v129
	v_lshl_add_u64 v[62:63], s[18:19], 0, v[128:129]
	v_lshlrev_b64 v[0:1], 13, v[60:61]
	v_or_b32_e32 v128, 4, v60
	v_lshl_add_u64 v[0:1], v[62:63], 0, v[0:1]
	v_lshlrev_b64 v[4:5], 13, v[128:129]
	global_load_dwordx4 v[0:3], v[0:1], off nt
	v_lshl_add_u64 v[4:5], v[62:63], 0, v[4:5]
	v_or_b32_e32 v128, 8, v60
	global_load_dwordx4 v[4:7], v[4:5], off nt
	v_lshlrev_b64 v[8:9], 13, v[128:129]
	v_lshl_add_u64 v[8:9], v[62:63], 0, v[8:9]
	v_or_b32_e32 v128, 12, v60
	global_load_dwordx4 v[8:11], v[8:9], off nt
	v_lshlrev_b64 v[12:13], 13, v[128:129]
	v_lshl_add_u64 v[12:13], v[62:63], 0, v[12:13]
	v_or_b32_e32 v128, 16, v60
	global_load_dwordx4 v[12:15], v[12:13], off nt
	v_lshlrev_b64 v[16:17], 13, v[128:129]
	v_lshl_add_u64 v[16:17], v[62:63], 0, v[16:17]
	v_or_b32_e32 v128, 20, v60
	global_load_dwordx4 v[16:19], v[16:17], off nt
	v_lshlrev_b64 v[20:21], 13, v[128:129]
	v_lshl_add_u64 v[20:21], v[62:63], 0, v[20:21]
	v_or_b32_e32 v128, 24, v60
	global_load_dwordx4 v[20:23], v[20:21], off nt
	v_lshlrev_b64 v[24:25], 13, v[128:129]
	v_lshl_add_u64 v[24:25], v[62:63], 0, v[24:25]
	v_or_b32_e32 v128, 28, v60
	global_load_dwordx4 v[24:27], v[24:25], off nt
	v_lshlrev_b64 v[28:29], 13, v[128:129]
	v_lshl_add_u64 v[28:29], v[62:63], 0, v[28:29]
	v_or_b32_e32 v128, 32, v60
	global_load_dwordx4 v[28:31], v[28:29], off nt
	v_lshlrev_b64 v[32:33], 13, v[128:129]
	v_lshl_add_u64 v[32:33], v[62:63], 0, v[32:33]
	v_or_b32_e32 v128, 36, v60
	global_load_dwordx4 v[32:35], v[32:33], off nt
	v_lshlrev_b64 v[36:37], 13, v[128:129]
	v_lshl_add_u64 v[36:37], v[62:63], 0, v[36:37]
	v_or_b32_e32 v128, 40, v60
	global_load_dwordx4 v[36:39], v[36:37], off nt
	v_lshlrev_b64 v[40:41], 13, v[128:129]
	v_lshl_add_u64 v[40:41], v[62:63], 0, v[40:41]
	v_or_b32_e32 v128, 44, v60
	global_load_dwordx4 v[40:43], v[40:41], off nt
	v_lshlrev_b64 v[44:45], 13, v[128:129]
	v_lshl_add_u64 v[44:45], v[62:63], 0, v[44:45]
	v_or_b32_e32 v128, 48, v60
	global_load_dwordx4 v[44:47], v[44:45], off nt
	v_lshlrev_b64 v[48:49], 13, v[128:129]
	v_lshl_add_u64 v[48:49], v[62:63], 0, v[48:49]
	v_or_b32_e32 v128, 52, v60
	global_load_dwordx4 v[48:51], v[48:49], off nt
	v_lshlrev_b64 v[52:53], 13, v[128:129]
	v_lshl_add_u64 v[52:53], v[62:63], 0, v[52:53]
	v_or_b32_e32 v128, 56, v60
	global_load_dwordx4 v[52:55], v[52:53], off nt
	v_lshlrev_b64 v[56:57], 13, v[128:129]
	v_lshl_add_u64 v[56:57], v[62:63], 0, v[56:57]
	v_or_b32_e32 v128, 60, v60
	global_load_dwordx4 v[56:59], v[56:57], off nt
	v_lshlrev_b64 v[60:61], 13, v[128:129]
	v_lshl_add_u64 v[60:61], v[62:63], 0, v[60:61]
	global_load_dwordx4 v[60:63], v[60:61], off nt
	s_lshl_b64 s[18:19], s[74:75], 1
	s_add_u32 s18, s15, s18
	s_addc_u32 s19, s34, s19
	v_lshlrev_b32_e32 v128, 1, v66
	v_readlane_b32 s74, v254, 61
	s_waitcnt vmcnt(0)
	ds_write2_b32 v71, v0, v1 offset1:1
	ds_write2_b32 v71, v2, v3 offset0:2 offset1:3
	v_add_u32_e32 v0, 0x410, v71
	ds_write2_b32 v0, v4, v5 offset1:1
	v_add_u32_e32 v0, 0x418, v71
	ds_write2_b32 v0, v6, v7 offset1:1
	v_add_u32_e32 v0, 0x820, v71
	ds_write2_b32 v0, v8, v9 offset1:1
	v_add_u32_e32 v0, 0x828, v71
	ds_write2_b32 v0, v10, v11 offset1:1
	v_add_u32_e32 v0, 0xc30, v71
	ds_write2_b32 v0, v12, v13 offset1:1
	v_add_u32_e32 v0, 0xc38, v71
	ds_write2_b32 v0, v14, v15 offset1:1
	v_add_u32_e32 v0, 0x1040, v71
	ds_write2_b32 v0, v16, v17 offset1:1
	v_add_u32_e32 v0, 0x1048, v71
	ds_write2_b32 v0, v18, v19 offset1:1
	v_add_u32_e32 v0, 0x1450, v71
	ds_write2_b32 v0, v20, v21 offset1:1
	v_add_u32_e32 v0, 0x1458, v71
	ds_write2_b32 v0, v22, v23 offset1:1
	v_add_u32_e32 v0, 0x1860, v71
	ds_write2_b32 v0, v24, v25 offset1:1
	v_add_u32_e32 v0, 0x1868, v71
	ds_write2_b32 v0, v26, v27 offset1:1
	v_add_u32_e32 v0, 0x1c70, v71
	ds_write2_b32 v0, v28, v29 offset1:1
	v_add_u32_e32 v0, 0x1c78, v71
	ds_write2_b32 v0, v30, v31 offset1:1
	v_add_u32_e32 v0, 0x2080, v71
	ds_write2_b32 v0, v32, v33 offset1:1
	v_add_u32_e32 v0, 0x2088, v71
	ds_write2_b32 v0, v34, v35 offset1:1
	v_add_u32_e32 v0, 0x2490, v71
	ds_write2_b32 v0, v36, v37 offset1:1
	v_add_u32_e32 v0, 0x2498, v71
	ds_write2_b32 v0, v38, v39 offset1:1
	v_add_u32_e32 v0, 0x28a0, v71
	ds_write2_b32 v0, v40, v41 offset1:1
	v_add_u32_e32 v0, 0x28a8, v71
	ds_write2_b32 v0, v42, v43 offset1:1
	v_add_u32_e32 v0, 0x2cb0, v71
	ds_write2_b32 v0, v44, v45 offset1:1
	v_add_u32_e32 v0, 0x2cb8, v71
	ds_write2_b32 v0, v46, v47 offset1:1
	v_add_u32_e32 v0, 0x30c0, v71
	ds_write2_b32 v0, v48, v49 offset1:1
	v_add_u32_e32 v0, 0x30c8, v71
	ds_write2_b32 v0, v50, v51 offset1:1
	v_add_u32_e32 v0, 0x34d0, v71
	ds_write2_b32 v0, v52, v53 offset1:1
	v_add_u32_e32 v0, 0x34d8, v71
	ds_write2_b32 v0, v54, v55 offset1:1
	v_add_u32_e32 v0, 0x38e0, v71
	ds_write2_b32 v0, v56, v57 offset1:1
	v_add_u32_e32 v0, 0x38e8, v71
	ds_write2_b32 v0, v58, v59 offset1:1
	v_add_u32_e32 v0, 0x3cf0, v71
	ds_write2_b32 v0, v60, v61 offset1:1
	v_add_u32_e32 v0, 0x3cf8, v71
	ds_write2_b32 v0, v62, v63 offset1:1
	s_waitcnt lgkmcnt(0)
; #define LAS __attribute__((address_space(3)))
; __device__ __forceinline__ unsigned cvtpk(float lo, float hi) { f32x2 v = {lo, hi}; bf16x2_t b = __builtin_convertvector(v, bf16x2_t); return __builtin_bit_cast(unsigned, b); }
; __device__ __forceinline__ void tr_item(const float* W, int K, int N, bf16_t* WT, const float* gain, int perm, LAS float* scr, int item, int lane) {
;     ...
;     const int c = lane & 7;
; #pragma unroll
;     for (int j = 0; j < 8; ++j) { const int n = (lane >> 3) + 8 * j; const LAS float* s = scr + (8 * c) * 65 + n;
;         u32x4 o; o.x = cvtpk(s[0 * 65], s[1 * 65]); o.y = cvtpk(s[2 * 65], s[3 * 65]); o.z = cvtpk(s[4 * 65], s[5 * 65]); o.w = cvtpk(s[6 * 65], s[7 * 65]);
;         const int ncol = n0 + n; int drow = ncol;
;         if (perm) { const int hf = ncol >= DFF ? 1 : 0, jj = ncol - hf * DFF; drow = 256 * (jj >> 7) + 128 * hf + (jj & 127); }
;         *(u32x4*)(WT + (size_t)drow * K + k0 + 8 * c) = o; }
;     asm volatile("s_waitcnt lgkmcnt(0)" ::: "memory");
	ds_read_b32 v2, v73
	ds_read_b32 v3, v73 offset:260
	v_lshl_add_u64 v[0:1], s[18:19], 0, v[128:129]
	s_mov_b64 s[18:19], 0x5600000
	v_lshl_add_u64 v[0:1], v[0:1], 0, s[18:19]
	v_or_b32_e32 v10, s6, v80
	s_waitcnt lgkmcnt(0)
	v_cvt_pk_bf16_f32 v2, v2, v3
	ds_read_b32 v3, v73 offset:520
	ds_read_b32 v4, v73 offset:780
	s_waitcnt lgkmcnt(0)
	v_cvt_pk_bf16_f32 v3, v3, v4
	ds_read_b32 v4, v73 offset:1040
	ds_read_b32 v5, v73 offset:1300
	s_waitcnt lgkmcnt(0)
	v_cvt_pk_bf16_f32 v4, v4, v5
	ds_read_b32 v5, v73 offset:1560
	ds_read_b32 v6, v73 offset:1820
	s_waitcnt lgkmcnt(0)
	v_cvt_pk_bf16_f32 v5, v5, v6
	v_or_b32_e32 v6, s6, v72
	v_lshlrev_b32_e32 v128, 12, v6
	v_lshl_add_u64 v[6:7], v[0:1], 0, v[128:129]
	flat_store_dwordx4 v[6:7], v[2:5]
	ds_read_b32 v2, v73 offset:32
	ds_read_b32 v3, v73 offset:292
	s_waitcnt lgkmcnt(0)
	v_cvt_pk_bf16_f32 v2, v2, v3
	ds_read_b32 v3, v73 offset:552
	ds_read_b32 v4, v73 offset:812
	s_waitcnt lgkmcnt(0)
	v_cvt_pk_bf16_f32 v3, v3, v4
	ds_read_b32 v4, v73 offset:1072
	ds_read_b32 v5, v73 offset:1332
	s_waitcnt lgkmcnt(0)
	v_cvt_pk_bf16_f32 v4, v4, v5
	ds_read_b32 v5, v73 offset:1592
	ds_read_b32 v6, v73 offset:1852
	s_waitcnt lgkmcnt(0)
	v_cvt_pk_bf16_f32 v5, v5, v6
	v_or_b32_e32 v6, s6, v74
	v_lshlrev_b32_e32 v128, 12, v6
	v_lshl_add_u64 v[6:7], v[0:1], 0, v[128:129]
	flat_store_dwordx4 v[6:7], v[2:5]
	ds_read_b32 v2, v73 offset:64
	ds_read_b32 v3, v73 offset:324
	s_waitcnt lgkmcnt(0)
	v_cvt_pk_bf16_f32 v2, v2, v3
	ds_read_b32 v3, v73 offset:584
	ds_read_b32 v4, v73 offset:844
	s_waitcnt lgkmcnt(0)
	v_cvt_pk_bf16_f32 v3, v3, v4
	ds_read_b32 v4, v73 offset:1104
	ds_read_b32 v5, v73 offset:1364
	s_waitcnt lgkmcnt(0)
	v_cvt_pk_bf16_f32 v4, v4, v5
	ds_read_b32 v5, v73 offset:1624
	ds_read_b32 v6, v73 offset:1884
	s_waitcnt lgkmcnt(0)
	v_cvt_pk_bf16_f32 v5, v5, v6
	v_or_b32_e32 v6, s6, v75
	v_lshlrev_b32_e32 v128, 12, v6
	v_lshl_add_u64 v[6:7], v[0:1], 0, v[128:129]
	flat_store_dwordx4 v[6:7], v[2:5]
	ds_read_b32 v2, v73 offset:96
	ds_read_b32 v3, v73 offset:356
	s_waitcnt lgkmcnt(0)
	v_cvt_pk_bf16_f32 v2, v2, v3
	ds_read_b32 v3, v73 offset:616
	ds_read_b32 v4, v73 offset:876
	s_waitcnt lgkmcnt(0)
	v_cvt_pk_bf16_f32 v3, v3, v4
	ds_read_b32 v4, v73 offset:1136
	ds_read_b32 v5, v73 offset:1396
	s_waitcnt lgkmcnt(0)
	v_cvt_pk_bf16_f32 v4, v4, v5
	ds_read_b32 v5, v73 offset:1656
	ds_read_b32 v6, v73 offset:1916
	s_waitcnt lgkmcnt(0)
	v_cvt_pk_bf16_f32 v5, v5, v6
	v_or_b32_e32 v6, s6, v76
	v_lshlrev_b32_e32 v128, 12, v6
	v_lshl_add_u64 v[6:7], v[0:1], 0, v[128:129]
	flat_store_dwordx4 v[6:7], v[2:5]
	ds_read_b32 v2, v73 offset:128
	ds_read_b32 v3, v73 offset:388
	s_waitcnt lgkmcnt(0)
	v_cvt_pk_bf16_f32 v2, v2, v3
	ds_read_b32 v3, v73 offset:648
	ds_read_b32 v4, v73 offset:908
	s_waitcnt lgkmcnt(0)
	v_cvt_pk_bf16_f32 v3, v3, v4
	ds_read_b32 v4, v73 offset:1168
	ds_read_b32 v5, v73 offset:1428
	s_waitcnt lgkmcnt(0)
	v_cvt_pk_bf16_f32 v4, v4, v5
	ds_read_b32 v5, v73 offset:1688
	ds_read_b32 v6, v73 offset:1948
	s_waitcnt lgkmcnt(0)
	v_cvt_pk_bf16_f32 v5, v5, v6
	v_or_b32_e32 v6, s6, v77
	v_lshlrev_b32_e32 v128, 12, v6
	v_lshl_add_u64 v[6:7], v[0:1], 0, v[128:129]
	flat_store_dwordx4 v[6:7], v[2:5]
	ds_read_b32 v2, v73 offset:160
	ds_read_b32 v3, v73 offset:420
	s_waitcnt lgkmcnt(0)
	v_cvt_pk_bf16_f32 v2, v2, v3
	ds_read_b32 v3, v73 offset:680
	ds_read_b32 v4, v73 offset:940
	s_waitcnt lgkmcnt(0)
	v_cvt_pk_bf16_f32 v3, v3, v4
	ds_read_b32 v4, v73 offset:1200
	ds_read_b32 v5, v73 offset:1460
	s_waitcnt lgkmcnt(0)
	v_cvt_pk_bf16_f32 v4, v4, v5
	ds_read_b32 v5, v73 offset:1720
	ds_read_b32 v6, v73 offset:1980
	s_waitcnt lgkmcnt(0)
	v_cvt_pk_bf16_f32 v5, v5, v6
	v_or_b32_e32 v6, s6, v78
	v_lshlrev_b32_e32 v128, 12, v6
	v_lshl_add_u64 v[6:7], v[0:1], 0, v[128:129]
	flat_store_dwordx4 v[6:7], v[2:5]
	ds_read_b32 v2, v73 offset:192
	ds_read_b32 v3, v73 offset:452
	s_waitcnt lgkmcnt(0)
	v_cvt_pk_bf16_f32 v2, v2, v3
	ds_read_b32 v3, v73 offset:712
	ds_read_b32 v4, v73 offset:972
	s_waitcnt lgkmcnt(0)
	v_cvt_pk_bf16_f32 v3, v3, v4
	ds_read_b32 v4, v73 offset:1232
	ds_read_b32 v5, v73 offset:1492
	s_waitcnt lgkmcnt(0)
	v_cvt_pk_bf16_f32 v4, v4, v5
	ds_read_b32 v5, v73 offset:1752
	ds_read_b32 v6, v73 offset:2012
	s_waitcnt lgkmcnt(0)
	v_cvt_pk_bf16_f32 v5, v5, v6
	v_or_b32_e32 v6, s6, v79
	v_lshlrev_b32_e32 v128, 12, v6
	v_lshl_add_u64 v[6:7], v[0:1], 0, v[128:129]
	flat_store_dwordx4 v[6:7], v[2:5]
	ds_read_b32 v2, v73 offset:224
	ds_read_b32 v3, v73 offset:484
	ds_read_b32 v4, v73 offset:744
	ds_read_b32 v5, v73 offset:1004
	ds_read_b32 v6, v73 offset:1264
	ds_read_b32 v7, v73 offset:1524
	ds_read_b32 v8, v73 offset:1784
	ds_read_b32 v9, v73 offset:2044
	v_lshlrev_b32_e32 v128, 12, v10
	s_waitcnt lgkmcnt(0)
	v_cvt_pk_bf16_f32 v2, v2, v3
	v_cvt_pk_bf16_f32 v3, v4, v5
	v_cvt_pk_bf16_f32 v4, v6, v7
	v_cvt_pk_bf16_f32 v5, v8, v9
	v_lshl_add_u64 v[0:1], v[0:1], 0, v[128:129]
	flat_store_dwordx4 v[0:1], v[2:5]
	s_waitcnt lgkmcnt(0)
	s_mov_b64 s[6:7], 0
; __device__ __forceinline__ void tr_item(const float* W, int K, int N, bf16_t* WT, const float* gain, int perm, LAS float* scr, int item, int lane) {
;     const int nblk = N / 64, kb = item / nblk, nb = item % nblk, k0 = 64 * kb, n0 = 64 * nb, lr = lane >> 4, c4 = lane & 15;
;     f32x4 v[16];
; #pragma unroll
;     for (int i = 0; i < 16; ++i) v[i] = *(const f32x4*)(W + (size_t)(k0 + lr + 4 * i) * N + n0 + 4 * c4);
;     if (gain) {
; #pragma unroll
;         for (int i = 0; i < 16; ++i) v[i] = v[i] * gain[k0 + lr + 4 * i];
;     }
; __global__ void __launch_bounds__(512, 2) mk_fwd(Args a) {
;     ...
;                 if (r < I_IN) { tr_item((const float*)a.in[7] + (size_t)l * DM * INW, DM, INW, (bf16_t*)((unsigned char*)wl + WT_IN), (const float*)a.in[6] + l * DM, 0, scr, r, lane); continue; } r -= I_IN;
.LBB0_613:
	s_andn2_b64 vcc, exec, s[6:7]
	s_cbranch_vccnz .LBB0_617
	s_and_b64 s[6:7], s[0:1], exec
	v_readlane_b32 s16, v254, 11
	s_cselect_b32 s6, 0x2800000, 0
	v_readlane_b32 s30, v254, 25
	v_readlane_b32 s31, v254, 26
	s_add_u32 s6, s30, s6
	v_readlane_b32 s17, v254, 12
	s_addc_u32 s7, s31, 0
	s_add_i32 s9, s8, 0xbe00
	s_and_b32 s17, s9, 0xffff
	v_readlane_b32 s18, v254, 13
	s_mul_i32 s17, s17, 0xcccd
	s_lshr_b32 s18, s17, 16
	s_lshr_b32 s17, s17, 22
	v_readlane_b32 s19, v254, 14
	s_mulk_i32 s17, 0x50
	s_sub_i32 s19, s9, s17
	s_and_b32 s9, s18, 0xffc0
	s_lshl_b32 s18, s19, 8
	s_lshl_b32 s17, s19, 6
	s_and_b32 s18, s18, 0x3ff00
	s_add_u32 s6, s6, s18
	v_or_b32_e32 v68, s9, v70
	s_addc_u32 s7, s7, 0
	v_lshlrev_b32_e32 v128, 2, v64
	v_lshl_add_u64 v[0:1], s[6:7], 0, v[128:129]
	s_movk_i32 s16, 0x5000
	v_or_b32_e32 v4, 4, v68
	v_mad_u64_u32 v[2:3], s[6:7], v68, s16, v[0:1]
	v_mad_u64_u32 v[4:5], s[6:7], v4, s16, v[0:1]
	global_load_dwordx4 v[60:63], v[2:3], off nt
	global_load_dwordx4 v[48:51], v[4:5], off nt
	v_or_b32_e32 v2, 8, v68
	v_or_b32_e32 v4, 12, v68
	v_mad_u64_u32 v[2:3], s[6:7], v2, s16, v[0:1]
	v_mad_u64_u32 v[4:5], s[6:7], v4, s16, v[0:1]
	global_load_dwordx4 v[56:59], v[2:3], off nt
	global_load_dwordx4 v[40:43], v[4:5], off nt
	v_or_b32_e32 v2, 16, v68
	v_or_b32_e32 v4, 20, v68
	v_mad_u64_u32 v[2:3], s[6:7], v2, s16, v[0:1]
	v_mad_u64_u32 v[4:5], s[6:7], v4, s16, v[0:1]
	global_load_dwordx4 v[52:55], v[2:3], off nt
	global_load_dwordx4 v[32:35], v[4:5], off nt
	v_or_b32_e32 v2, 24, v68
	v_or_b32_e32 v4, 28, v68
	v_mad_u64_u32 v[2:3], s[6:7], v2, s16, v[0:1]
	v_mad_u64_u32 v[4:5], s[6:7], v4, s16, v[0:1]
	global_load_dwordx4 v[44:47], v[2:3], off nt
	global_load_dwordx4 v[24:27], v[4:5], off nt
	v_or_b32_e32 v2, 32, v68
	v_or_b32_e32 v4, 36, v68
	v_mad_u64_u32 v[2:3], s[6:7], v2, s16, v[0:1]
	v_mad_u64_u32 v[4:5], s[6:7], v4, s16, v[0:1]
	global_load_dwordx4 v[36:39], v[2:3], off nt
	global_load_dwordx4 v[12:15], v[4:5], off nt
	v_or_b32_e32 v2, 40, v68
	v_or_b32_e32 v4, 44, v68
	v_mad_u64_u32 v[2:3], s[6:7], v2, s16, v[0:1]
	v_mad_u64_u32 v[4:5], s[6:7], v4, s16, v[0:1]
	global_load_dwordx4 v[28:31], v[2:3], off nt
	global_load_dwordx4 v[8:11], v[4:5], off nt
	v_or_b32_e32 v2, 48, v68
	v_or_b32_e32 v4, 52, v68
	v_mad_u64_u32 v[2:3], s[6:7], v2, s16, v[0:1]
	v_mad_u64_u32 v[4:5], s[6:7], v4, s16, v[0:1]
	global_load_dwordx4 v[20:23], v[2:3], off nt
	s_nop 0
	global_load_dwordx4 v[4:7], v[4:5], off nt
	v_or_b32_e32 v2, 56, v68
	v_or_b32_e32 v16, 60, v68
	v_mad_u64_u32 v[2:3], s[6:7], v2, s16, v[0:1]
	v_mad_u64_u32 v[0:1], s[6:7], v16, s16, v[0:1]
	global_load_dwordx4 v[16:19], v[2:3], off nt
	s_nop 0
	global_load_dwordx4 v[0:3], v[0:1], off nt
	v_readlane_b32 s6, v254, 2
	v_readlane_b32 s7, v254, 3
	v_readlane_b32 s28, v254, 23
	v_readlane_b32 s29, v254, 24
	s_andn2_b64 vcc, exec, s[6:7]
	v_readlane_b32 s20, v254, 15
	v_readlane_b32 s21, v254, 16
	v_readlane_b32 s22, v254, 17
	v_readlane_b32 s23, v254, 18
	v_readlane_b32 s24, v254, 19
	v_readlane_b32 s25, v254, 20
	v_readlane_b32 s26, v254, 21
	v_readlane_b32 s27, v254, 22
	s_cbranch_vccnz .LBB0_616
	s_and_b64 s[6:7], s[0:1], exec
	s_cselect_b32 s6, 0x2000, 0
	s_add_u32 s6, s28, s6
	s_addc_u32 s7, s29, 0
	v_lshlrev_b32_e32 v69, 2, v68
	global_load_dword v84, v69, s[6:7]
	global_load_dword v86, v69, s[6:7] offset:16
	global_load_dword v88, v69, s[6:7] offset:32
	global_load_dword v90, v69, s[6:7] offset:48
	global_load_dword v92, v69, s[6:7] offset:64
	global_load_dword v94, v69, s[6:7] offset:80
	global_load_dword v96, v69, s[6:7] offset:96
	global_load_dword v98, v69, s[6:7] offset:112
	global_load_dword v100, v69, s[6:7] offset:128
	global_load_dword v102, v69, s[6:7] offset:144
	global_load_dword v104, v69, s[6:7] offset:160
	global_load_dword v106, v69, s[6:7] offset:176
	global_load_dword v108, v69, s[6:7] offset:192
	global_load_dword v110, v69, s[6:7] offset:208
	global_load_dword v112, v69, s[6:7] offset:224
	global_load_dword v114, v69, s[6:7] offset:240
	s_waitcnt vmcnt(0)
	v_pk_mul_f32 v[62:63], v[62:63], v[84:85] op_sel_hi:[1,0]
	v_pk_mul_f32 v[60:61], v[60:61], v[84:85] op_sel_hi:[1,0]
	v_pk_mul_f32 v[50:51], v[50:51], v[86:87] op_sel_hi:[1,0]
	v_pk_mul_f32 v[48:49], v[48:49], v[86:87] op_sel_hi:[1,0]
	v_pk_mul_f32 v[58:59], v[58:59], v[88:89] op_sel_hi:[1,0]
	v_pk_mul_f32 v[56:57], v[56:57], v[88:89] op_sel_hi:[1,0]
	v_pk_mul_f32 v[42:43], v[42:43], v[90:91] op_sel_hi:[1,0]
	v_pk_mul_f32 v[40:41], v[40:41], v[90:91] op_sel_hi:[1,0]
	v_pk_mul_f32 v[54:55], v[54:55], v[92:93] op_sel_hi:[1,0]
	v_pk_mul_f32 v[52:53], v[52:53], v[92:93] op_sel_hi:[1,0]
	v_pk_mul_f32 v[34:35], v[34:35], v[94:95] op_sel_hi:[1,0]
	v_pk_mul_f32 v[32:33], v[32:33], v[94:95] op_sel_hi:[1,0]
	v_pk_mul_f32 v[46:47], v[46:47], v[96:97] op_sel_hi:[1,0]
	v_pk_mul_f32 v[44:45], v[44:45], v[96:97] op_sel_hi:[1,0]
	v_pk_mul_f32 v[26:27], v[26:27], v[98:99] op_sel_hi:[1,0]
	v_pk_mul_f32 v[24:25], v[24:25], v[98:99] op_sel_hi:[1,0]
	v_pk_mul_f32 v[38:39], v[38:39], v[100:101] op_sel_hi:[1,0]
	v_pk_mul_f32 v[36:37], v[36:37], v[100:101] op_sel_hi:[1,0]
	v_pk_mul_f32 v[14:15], v[14:15], v[102:103] op_sel_hi:[1,0]
	v_pk_mul_f32 v[12:13], v[12:13], v[102:103] op_sel_hi:[1,0]
	v_pk_mul_f32 v[30:31], v[30:31], v[104:105] op_sel_hi:[1,0]
	v_pk_mul_f32 v[28:29], v[28:29], v[104:105] op_sel_hi:[1,0]
	v_pk_mul_f32 v[10:11], v[10:11], v[106:107] op_sel_hi:[1,0]
	v_pk_mul_f32 v[8:9], v[8:9], v[106:107] op_sel_hi:[1,0]
	v_pk_mul_f32 v[22:23], v[22:23], v[108:109] op_sel_hi:[1,0]
	v_pk_mul_f32 v[20:21], v[20:21], v[108:109] op_sel_hi:[1,0]
	v_pk_mul_f32 v[6:7], v[6:7], v[110:111] op_sel_hi:[1,0]
	v_pk_mul_f32 v[4:5], v[4:5], v[110:111] op_sel_hi:[1,0]
	v_pk_mul_f32 v[18:19], v[18:19], v[112:113] op_sel_hi:[1,0]
	v_pk_mul_f32 v[16:17], v[16:17], v[112:113] op_sel_hi:[1,0]
	v_pk_mul_f32 v[2:3], v[2:3], v[114:115] op_sel_hi:[1,0]
	v_pk_mul_f32 v[0:1], v[0:1], v[114:115] op_sel_hi:[1,0]

; __device__ __forceinline__ void tr_item(const float* W, int K, int N, bf16_t* WT, const float* gain, int perm, LAS float* scr, int item, int lane) {
;     const int nblk = N / 64, kb = item / nblk, nb = item % nblk, k0 = 64 * kb, n0 = 64 * nb, lr = lane >> 4, c4 = lane & 15;
;     f32x4 v[16];
; #pragma unroll
;     for (int i = 0; i < 16; ++i) v[i] = *(const f32x4*)(W + (size_t)(k0 + lr + 4 * i) * N + n0 + 4 * c4);
;     if (gain) {
; #pragma unroll
;         for (int i = 0; i < 16; ++i) v[i] = v[i] * gain[k0 + lr + 4 * i];
;     }
; #pragma unroll
;     for (int i = 0; i < 16; ++i)
; #pragma unroll
;         for (int e = 0; e < 4; ++e) scr[(lr + 4 * i) * 65 + 4 * c4 + e] = v[i][e];
;     asm volatile("s_waitcnt lgkmcnt(0)" ::: "memory");
; __global__ void __launch_bounds__(512, 2) mk_fwd(Args a) {
;     ...
;                 if (r < I_D) { tr_item((const float*)a.in[18] + (size_t)l * DFF * DM, DFF, DM, (bf16_t*)((unsigned char*)wl + WT_D2), nullptr, 0, scr, r, lane); continue; } r -= I_D;
.LBB0_618:
	s_andn2_b64 vcc, exec, s[6:7]
	s_cbranch_vccnz .LBB0_620
	s_and_b64 s[6:7], s[0:1], exec
	s_cselect_b32 s6, 0x2c00000, 0
	s_add_u32 s7, s56, s6
	s_addc_u32 s9, s57, 0
	s_lshl_b32 s6, s8, 1
	s_add_i32 s6, s6, 0x19200
	s_and_b32 s17, s6, 0x1ffc0
	s_and_b32 s6, s12, 0x7c0
	s_lshl_b32 s18, s6, 2
	s_add_u32 s18, s7, s18
	v_or_b32_e32 v2, s17, v70
	s_addc_u32 s19, s9, 0
	v_lshlrev_b32_e32 v128, 2, v64
	v_lshl_add_u64 v[0:1], s[18:19], 0, v[128:129]
	v_lshlrev_b32_e32 v128, 13, v2
	v_lshl_add_u64 v[60:61], v[0:1], 0, v[128:129]
	s_mov_b32 s7, 0x8000
	v_add_co_u32_e32 v4, vcc, s7, v60
	s_mov_b32 s7, 0x10000
	s_nop 0
	v_addc_co_u32_e32 v5, vcc, 0, v61, vcc
	v_add_co_u32_e32 v8, vcc, s7, v60
	global_load_dwordx4 v[0:3], v[60:61], off nt
	s_nop 0
	global_load_dwordx4 v[4:7], v[4:5], off nt
	v_addc_co_u32_e32 v9, vcc, 0, v61, vcc
	s_mov_b32 s7, 0x18000
	v_add_co_u32_e32 v12, vcc, s7, v60
	s_mov_b32 s7, 0x20000
	s_nop 0
	v_addc_co_u32_e32 v13, vcc, 0, v61, vcc
	global_load_dwordx4 v[8:11], v[8:9], off nt
	s_nop 0
	global_load_dwordx4 v[12:15], v[12:13], off nt
	v_add_co_u32_e32 v16, vcc, s7, v60
	s_mov_b32 s7, 0x28000
	s_nop 0
	v_addc_co_u32_e32 v17, vcc, 0, v61, vcc
	v_add_co_u32_e32 v20, vcc, s7, v60
	s_mov_b32 s7, 0x30000
	s_nop 0
	v_addc_co_u32_e32 v21, vcc, 0, v61, vcc
	global_load_dwordx4 v[16:19], v[16:17], off nt
	s_nop 0
	global_load_dwordx4 v[20:23], v[20:21], off nt
	v_add_co_u32_e32 v24, vcc, s7, v60
	s_mov_b32 s7, 0x38000
	s_nop 0
	v_addc_co_u32_e32 v25, vcc, 0, v61, vcc
	v_add_co_u32_e32 v28, vcc, s7, v60
	s_mov_b32 s7, 0x40000
	s_nop 0
	v_addc_co_u32_e32 v29, vcc, 0, v61, vcc
	global_load_dwordx4 v[24:27], v[24:25], off nt
	s_nop 0
	global_load_dwordx4 v[28:31], v[28:29], off nt
	v_add_co_u32_e32 v32, vcc, s7, v60
	s_mov_b32 s7, 0x48000
	s_nop 0
	v_addc_co_u32_e32 v33, vcc, 0, v61, vcc
	v_add_co_u32_e32 v36, vcc, s7, v60
	s_mov_b32 s7, 0x50000
	s_nop 0
	v_addc_co_u32_e32 v37, vcc, 0, v61, vcc
	global_load_dwordx4 v[32:35], v[32:33], off nt
	s_nop 0
	global_load_dwordx4 v[36:39], v[36:37], off nt
	v_add_co_u32_e32 v40, vcc, s7, v60
	s_mov_b32 s7, 0x58000
	s_nop 0
	v_addc_co_u32_e32 v41, vcc, 0, v61, vcc
	v_add_co_u32_e32 v44, vcc, s7, v60
	s_mov_b32 s7, 0x60000
	s_nop 0
	v_addc_co_u32_e32 v45, vcc, 0, v61, vcc
	global_load_dwordx4 v[40:43], v[40:41], off nt
	s_nop 0
	global_load_dwordx4 v[44:47], v[44:45], off nt
	v_add_co_u32_e32 v48, vcc, s7, v60
	s_mov_b32 s7, 0x68000
	s_nop 0
	v_addc_co_u32_e32 v49, vcc, 0, v61, vcc
	global_load_dwordx4 v[48:51], v[48:49], off nt
	v_add_co_u32_e32 v52, vcc, s7, v60
	s_mov_b32 s7, 0x70000
	s_nop 0
	v_addc_co_u32_e32 v53, vcc, 0, v61, vcc
	global_load_dwordx4 v[52:55], v[52:53], off nt
	v_add_co_u32_e32 v56, vcc, s7, v60
	s_mov_b32 s7, 0x78000
	s_nop 0
	v_addc_co_u32_e32 v57, vcc, 0, v61, vcc
	global_load_dwordx4 v[56:59], v[56:57], off nt
	v_add_co_u32_e32 v60, vcc, s7, v60
	s_lshl_b32 s7, s17, 1
	s_nop 0
	v_addc_co_u32_e32 v61, vcc, 0, v61, vcc
	global_load_dwordx4 v[60:63], v[60:61], off nt
	s_waitcnt vmcnt(0)
	ds_write2_b32 v71, v0, v1 offset1:1
	ds_write2_b32 v71, v2, v3 offset0:2 offset1:3
	v_add_u32_e32 v0, 0x410, v71
	ds_write2_b32 v0, v4, v5 offset1:1
	v_add_u32_e32 v0, 0x418, v71
	ds_write2_b32 v0, v6, v7 offset1:1
	v_add_u32_e32 v0, 0x820, v71
	s_add_u32 s18, s15, s7
	s_addc_u32 s19, s34, 0
	v_lshlrev_b32_e32 v128, 1, v66
	ds_write2_b32 v0, v8, v9 offset1:1
	v_add_u32_e32 v0, 0x828, v71
	ds_write2_b32 v0, v10, v11 offset1:1
	v_add_u32_e32 v0, 0xc30, v71
	ds_write2_b32 v0, v12, v13 offset1:1
	v_add_u32_e32 v0, 0xc38, v71
	ds_write2_b32 v0, v14, v15 offset1:1
	v_add_u32_e32 v0, 0x1040, v71
	ds_write2_b32 v0, v16, v17 offset1:1
	v_add_u32_e32 v0, 0x1048, v71
	ds_write2_b32 v0, v18, v19 offset1:1
	v_add_u32_e32 v0, 0x1450, v71
	ds_write2_b32 v0, v20, v21 offset1:1
	v_add_u32_e32 v0, 0x1458, v71
	ds_write2_b32 v0, v22, v23 offset1:1
	v_add_u32_e32 v0, 0x1860, v71
	ds_write2_b32 v0, v24, v25 offset1:1
	v_add_u32_e32 v0, 0x1868, v71
	ds_write2_b32 v0, v26, v27 offset1:1
	v_add_u32_e32 v0, 0x1c70, v71
	ds_write2_b32 v0, v28, v29 offset1:1
	v_add_u32_e32 v0, 0x1c78, v71
	ds_write2_b32 v0, v30, v31 offset1:1
	v_add_u32_e32 v0, 0x2080, v71
	ds_write2_b32 v0, v32, v33 offset1:1
	v_add_u32_e32 v0, 0x2088, v71
	ds_write2_b32 v0, v34, v35 offset1:1
	v_add_u32_e32 v0, 0x2490, v71
	ds_write2_b32 v0, v36, v37 offset1:1
	v_add_u32_e32 v0, 0x2498, v71
	ds_write2_b32 v0, v38, v39 offset1:1
	v_add_u32_e32 v0, 0x28a0, v71
	ds_write2_b32 v0, v40, v41 offset1:1
	v_add_u32_e32 v0, 0x28a8, v71
	ds_write2_b32 v0, v42, v43 offset1:1
	v_add_u32_e32 v0, 0x2cb0, v71
	ds_write2_b32 v0, v44, v45 offset1:1
	v_add_u32_e32 v0, 0x2cb8, v71
	ds_write2_b32 v0, v46, v47 offset1:1
	v_add_u32_e32 v0, 0x30c0, v71
	ds_write2_b32 v0, v48, v49 offset1:1
	v_add_u32_e32 v0, 0x30c8, v71
	ds_write2_b32 v0, v50, v51 offset1:1
	v_add_u32_e32 v0, 0x34d0, v71
	ds_write2_b32 v0, v52, v53 offset1:1
	v_add_u32_e32 v0, 0x34d8, v71
	ds_write2_b32 v0, v54, v55 offset1:1
	v_add_u32_e32 v0, 0x38e0, v71
	ds_write2_b32 v0, v56, v57 offset1:1
	v_add_u32_e32 v0, 0x38e8, v71
	ds_write2_b32 v0, v58, v59 offset1:1
	v_add_u32_e32 v0, 0x3cf0, v71
	ds_write2_b32 v0, v60, v61 offset1:1
	v_add_u32_e32 v0, 0x3cf8, v71
	ds_write2_b32 v0, v62, v63 offset1:1
	s_waitcnt lgkmcnt(0)
; #define LAS __attribute__((address_space(3)))
; __device__ __forceinline__ unsigned cvtpk(float lo, float hi) { f32x2 v = {lo, hi}; bf16x2_t b = __builtin_convertvector(v, bf16x2_t); return __builtin_bit_cast(unsigned, b); }
; __device__ __forceinline__ void tr_item(const float* W, int K, int N, bf16_t* WT, const float* gain, int perm, LAS float* scr, int item, int lane) {
;     ...
;     const int c = lane & 7;
; #pragma unroll
;     for (int j = 0; j < 8; ++j) { const int n = (lane >> 3) + 8 * j; const LAS float* s = scr + (8 * c) * 65 + n;
;         u32x4 o; o.x = cvtpk(s[0 * 65], s[1 * 65]); o.y = cvtpk(s[2 * 65], s[3 * 65]); o.z = cvtpk(s[4 * 65], s[5 * 65]); o.w = cvtpk(s[6 * 65], s[7 * 65]);
;         const int ncol = n0 + n; int drow = ncol;
;         if (perm) { const int hf = ncol >= DFF ? 1 : 0, jj = ncol - hf * DFF; drow = 256 * (jj >> 7) + 128 * hf + (jj & 127); }
;         *(u32x4*)(WT + (size_t)drow * K + k0 + 8 * c) = o; }
;     asm volatile("s_waitcnt lgkmcnt(0)" ::: "memory");
	ds_read_b32 v2, v73
	ds_read_b32 v3, v73 offset:260
	ds_read_b32 v6, v73 offset:520
	ds_read_b32 v7, v73 offset:780
	ds_read_b32 v8, v73 offset:1040
	ds_read_b32 v9, v73 offset:1300
	ds_read_b32 v10, v73 offset:1560
	ds_read_b32 v11, v73 offset:1820
	v_lshl_add_u64 v[0:1], s[18:19], 0, v[128:129]
	s_mov_b64 s[18:19], 0x8a00000
	v_lshl_add_u64 v[4:5], v[0:1], 0, s[18:19]
	s_waitcnt lgkmcnt(0)
	v_cvt_pk_bf16_f32 v1, v6, v7
	v_or_b32_e32 v6, s6, v72
	v_mul_u32_u24_e32 v6, 0x1600, v6
	v_lshlrev_b32_e32 v128, 1, v6
	v_cvt_pk_bf16_f32 v0, v2, v3
	v_cvt_pk_bf16_f32 v2, v8, v9
	v_cvt_pk_bf16_f32 v3, v10, v11
	v_lshl_add_u64 v[6:7], v[4:5], 0, v[128:129]
	flat_store_dwordx4 v[6:7], v[0:3]
	ds_read_b32 v0, v73 offset:32
	ds_read_b32 v1, v73 offset:292
	ds_read_b32 v2, v73 offset:552
	ds_read_b32 v3, v73 offset:812
	ds_read_b32 v6, v73 offset:1072
	ds_read_b32 v7, v73 offset:1332
	ds_read_b32 v8, v73 offset:1592
	ds_read_b32 v9, v73 offset:1852
	s_waitcnt lgkmcnt(0)
	v_cvt_pk_bf16_f32 v0, v0, v1
	v_cvt_pk_bf16_f32 v1, v2, v3
	v_cvt_pk_bf16_f32 v2, v6, v7
	v_or_b32_e32 v6, s6, v74
	v_mul_u32_u24_e32 v6, 0x1600, v6
	v_lshlrev_b32_e32 v128, 1, v6
	v_cvt_pk_bf16_f32 v3, v8, v9
	v_lshl_add_u64 v[6:7], v[4:5], 0, v[128:129]
	flat_store_dwordx4 v[6:7], v[0:3]
	ds_read_b32 v0, v73 offset:64
	ds_read_b32 v1, v73 offset:324
	ds_read_b32 v2, v73 offset:584
	ds_read_b32 v3, v73 offset:844
	ds_read_b32 v6, v73 offset:1104
	ds_read_b32 v7, v73 offset:1364
	ds_read_b32 v8, v73 offset:1624
	ds_read_b32 v9, v73 offset:1884
	s_waitcnt lgkmcnt(0)
	v_cvt_pk_bf16_f32 v0, v0, v1
	v_cvt_pk_bf16_f32 v1, v2, v3
	v_cvt_pk_bf16_f32 v2, v6, v7
	v_or_b32_e32 v6, s6, v75
	v_mul_u32_u24_e32 v6, 0x1600, v6
	v_lshlrev_b32_e32 v128, 1, v6
	v_cvt_pk_bf16_f32 v3, v8, v9
	v_lshl_add_u64 v[6:7], v[4:5], 0, v[128:129]
	flat_store_dwordx4 v[6:7], v[0:3]
	ds_read_b32 v0, v73 offset:96
	ds_read_b32 v1, v73 offset:356
	ds_read_b32 v2, v73 offset:616
	ds_read_b32 v3, v73 offset:876
	ds_read_b32 v6, v73 offset:1136
	ds_read_b32 v7, v73 offset:1396
	ds_read_b32 v8, v73 offset:1656
	ds_read_b32 v9, v73 offset:1916
	s_waitcnt lgkmcnt(0)
	v_cvt_pk_bf16_f32 v0, v0, v1
	v_cvt_pk_bf16_f32 v1, v2, v3
	v_cvt_pk_bf16_f32 v2, v6, v7
	v_or_b32_e32 v6, s6, v76
	v_mul_u32_u24_e32 v6, 0x1600, v6
	v_lshlrev_b32_e32 v128, 1, v6
	v_cvt_pk_bf16_f32 v3, v8, v9
	v_lshl_add_u64 v[6:7], v[4:5], 0, v[128:129]
	flat_store_dwordx4 v[6:7], v[0:3]
	ds_read_b32 v0, v73 offset:128
	ds_read_b32 v1, v73 offset:388
	ds_read_b32 v2, v73 offset:648
	ds_read_b32 v3, v73 offset:908
	ds_read_b32 v6, v73 offset:1168
	ds_read_b32 v7, v73 offset:1428
	ds_read_b32 v8, v73 offset:1688
	ds_read_b32 v9, v73 offset:1948
	s_waitcnt lgkmcnt(0)
	v_cvt_pk_bf16_f32 v0, v0, v1
	v_cvt_pk_bf16_f32 v1, v2, v3
	v_cvt_pk_bf16_f32 v2, v6, v7
	v_or_b32_e32 v6, s6, v77
	v_mul_u32_u24_e32 v6, 0x1600, v6
	v_lshlrev_b32_e32 v128, 1, v6
	v_cvt_pk_bf16_f32 v3, v8, v9
	v_lshl_add_u64 v[6:7], v[4:5], 0, v[128:129]
	flat_store_dwordx4 v[6:7], v[0:3]
	ds_read_b32 v0, v73 offset:160
	ds_read_b32 v1, v73 offset:420
	ds_read_b32 v2, v73 offset:680
	ds_read_b32 v3, v73 offset:940
	ds_read_b32 v6, v73 offset:1200
	ds_read_b32 v7, v73 offset:1460
	ds_read_b32 v8, v73 offset:1720
	ds_read_b32 v9, v73 offset:1980
	s_waitcnt lgkmcnt(0)
	v_cvt_pk_bf16_f32 v0, v0, v1
	v_cvt_pk_bf16_f32 v1, v2, v3
	v_cvt_pk_bf16_f32 v2, v6, v7
	v_or_b32_e32 v6, s6, v78
	v_mul_u32_u24_e32 v6, 0x1600, v6
	v_lshlrev_b32_e32 v128, 1, v6
	v_cvt_pk_bf16_f32 v3, v8, v9
	v_lshl_add_u64 v[6:7], v[4:5], 0, v[128:129]
	flat_store_dwordx4 v[6:7], v[0:3]
	ds_read_b32 v0, v73 offset:192
	ds_read_b32 v1, v73 offset:452
	ds_read_b32 v2, v73 offset:712
	ds_read_b32 v3, v73 offset:972
	ds_read_b32 v6, v73 offset:1232
	ds_read_b32 v7, v73 offset:1492
	ds_read_b32 v8, v73 offset:1752
	ds_read_b32 v9, v73 offset:2012
	s_waitcnt lgkmcnt(0)
	v_cvt_pk_bf16_f32 v0, v0, v1
	v_cvt_pk_bf16_f32 v1, v2, v3
	v_cvt_pk_bf16_f32 v2, v6, v7
	v_or_b32_e32 v6, s6, v79
	v_mul_u32_u24_e32 v6, 0x1600, v6
	v_lshlrev_b32_e32 v128, 1, v6
	v_cvt_pk_bf16_f32 v3, v8, v9
	v_lshl_add_u64 v[6:7], v[4:5], 0, v[128:129]
	flat_store_dwordx4 v[6:7], v[0:3]
	ds_read_b32 v0, v73 offset:224
	ds_read_b32 v1, v73 offset:484
	ds_read_b32 v2, v73 offset:744
	ds_read_b32 v3, v73 offset:1004
	ds_read_b32 v6, v73 offset:1264
	ds_read_b32 v7, v73 offset:1524
	ds_read_b32 v8, v73 offset:1784
	ds_read_b32 v9, v73 offset:2044
	v_or_b32_e32 v10, s6, v80
	s_waitcnt lgkmcnt(0)
	v_cvt_pk_bf16_f32 v0, v0, v1
	v_cvt_pk_bf16_f32 v1, v2, v3
	v_cvt_pk_bf16_f32 v2, v6, v7
	v_mul_u32_u24_e32 v6, 0x1600, v10
	v_lshlrev_b32_e32 v128, 1, v6
	v_cvt_pk_bf16_f32 v3, v8, v9
	v_lshl_add_u64 v[4:5], v[4:5], 0, v[128:129]
	flat_store_dwordx4 v[4:5], v[0:3]
	s_waitcnt lgkmcnt(0)

; __device__ __forceinline__ void tr_item(const float* W, int K, int N, bf16_t* WT, const float* gain, int perm, LAS float* scr, int item, int lane) {
;     const int nblk = N / 64, kb = item / nblk, nb = item % nblk, k0 = 64 * kb, n0 = 64 * nb, lr = lane >> 4, c4 = lane & 15;
;     f32x4 v[16];
; #pragma unroll
;     for (int i = 0; i < 16; ++i) v[i] = *(const f32x4*)(W + (size_t)(k0 + lr + 4 * i) * N + n0 + 4 * c4);
;     if (gain) {
; #pragma unroll
;         for (int i = 0; i < 16; ++i) v[i] = v[i] * gain[k0 + lr + 4 * i];
;     }
; #pragma unroll
;     for (int i = 0; i < 16; ++i)
; #pragma unroll
;         for (int e = 0; e < 4; ++e) scr[(lr + 4 * i) * 65 + 4 * c4 + e] = v[i][e];
;     asm volatile("s_waitcnt lgkmcnt(0)" ::: "memory");
; __global__ void __launch_bounds__(512, 2) mk_fwd(Args a) {
;     ...
;                 if (r < I_D) { tr_item((const float*)a.in[5] + (size_t)l * DFF * DM, DFF, DM, (bf16_t*)((unsigned char*)wl + WT_D1), nullptr, 0, scr, r, lane); continue; } r -= I_D;
.LBB0_621:
	s_andn2_b64 vcc, exec, s[6:7]
	s_cbranch_vccnz .LBB0_623
	s_and_b64 s[6:7], s[0:1], exec
	v_readlane_b32 s16, v254, 11
	s_cselect_b32 s6, 0x2c00000, 0
	v_readlane_b32 s26, v254, 21
	v_readlane_b32 s27, v254, 22
	s_add_u32 s7, s26, s6
	s_addc_u32 s9, s27, 0
	s_lshl_b32 s6, s8, 1
	v_readlane_b32 s17, v254, 12
	s_add_i32 s6, s6, 0x1a800
	v_readlane_b32 s18, v254, 13
	s_and_b32 s17, s6, 0x1ffc0
	s_and_b32 s6, s12, 0x7c0
	s_lshl_b32 s18, s6, 2
	v_readlane_b32 s19, v254, 14
	s_add_u32 s18, s7, s18
	v_or_b32_e32 v2, s17, v70
	s_addc_u32 s19, s9, 0
	v_lshlrev_b32_e32 v128, 2, v64
	v_lshl_add_u64 v[0:1], s[18:19], 0, v[128:129]
	v_lshlrev_b32_e32 v128, 13, v2
	v_lshl_add_u64 v[60:61], v[0:1], 0, v[128:129]
	s_mov_b32 s7, 0x8000
	v_add_co_u32_e32 v4, vcc, s7, v60
	s_mov_b32 s7, 0x10000
	s_nop 0
	v_addc_co_u32_e32 v5, vcc, 0, v61, vcc
	v_add_co_u32_e32 v8, vcc, s7, v60
	global_load_dwordx4 v[0:3], v[60:61], off nt
	s_nop 0
	global_load_dwordx4 v[4:7], v[4:5], off nt
	v_addc_co_u32_e32 v9, vcc, 0, v61, vcc
	s_mov_b32 s7, 0x18000
	v_add_co_u32_e32 v12, vcc, s7, v60
	s_mov_b32 s7, 0x20000
	s_nop 0
	v_addc_co_u32_e32 v13, vcc, 0, v61, vcc
	global_load_dwordx4 v[8:11], v[8:9], off nt
	s_nop 0
	global_load_dwordx4 v[12:15], v[12:13], off nt
	v_add_co_u32_e32 v16, vcc, s7, v60
	s_mov_b32 s7, 0x28000
	s_nop 0
	v_addc_co_u32_e32 v17, vcc, 0, v61, vcc
	v_add_co_u32_e32 v20, vcc, s7, v60
	s_mov_b32 s7, 0x30000
	s_nop 0
	v_addc_co_u32_e32 v21, vcc, 0, v61, vcc
	global_load_dwordx4 v[16:19], v[16:17], off nt
	s_nop 0
	global_load_dwordx4 v[20:23], v[20:21], off nt
	v_add_co_u32_e32 v24, vcc, s7, v60
	s_mov_b32 s7, 0x38000
	s_nop 0
	v_addc_co_u32_e32 v25, vcc, 0, v61, vcc
	v_add_co_u32_e32 v28, vcc, s7, v60
	s_mov_b32 s7, 0x40000
	s_nop 0
	v_addc_co_u32_e32 v29, vcc, 0, v61, vcc
	global_load_dwordx4 v[24:27], v[24:25], off nt
	s_nop 0
	global_load_dwordx4 v[28:31], v[28:29], off nt
	v_add_co_u32_e32 v32, vcc, s7, v60
	s_mov_b32 s7, 0x48000
	s_nop 0
	v_addc_co_u32_e32 v33, vcc, 0, v61, vcc
	v_add_co_u32_e32 v36, vcc, s7, v60
	s_mov_b32 s7, 0x50000
	s_nop 0
	v_addc_co_u32_e32 v37, vcc, 0, v61, vcc
	global_load_dwordx4 v[32:35], v[32:33], off nt
	s_nop 0
	global_load_dwordx4 v[36:39], v[36:37], off nt
	v_add_co_u32_e32 v40, vcc, s7, v60
	s_mov_b32 s7, 0x58000
	s_nop 0
	v_addc_co_u32_e32 v41, vcc, 0, v61, vcc
	v_add_co_u32_e32 v44, vcc, s7, v60
	s_mov_b32 s7, 0x60000
	s_nop 0
	v_addc_co_u32_e32 v45, vcc, 0, v61, vcc
	global_load_dwordx4 v[40:43], v[40:41], off nt
	s_nop 0
	global_load_dwordx4 v[44:47], v[44:45], off nt
	v_add_co_u32_e32 v48, vcc, s7, v60
	s_mov_b32 s7, 0x68000
	s_nop 0
	v_addc_co_u32_e32 v49, vcc, 0, v61, vcc
	global_load_dwordx4 v[48:51], v[48:49], off nt
	v_add_co_u32_e32 v52, vcc, s7, v60
	s_mov_b32 s7, 0x70000
	s_nop 0
	v_addc_co_u32_e32 v53, vcc, 0, v61, vcc
	global_load_dwordx4 v[52:55], v[52:53], off nt
	v_add_co_u32_e32 v56, vcc, s7, v60
	s_mov_b32 s7, 0x78000
	s_nop 0
	v_addc_co_u32_e32 v57, vcc, 0, v61, vcc
	global_load_dwordx4 v[56:59], v[56:57], off nt
	v_add_co_u32_e32 v60, vcc, s7, v60
	s_lshl_b32 s7, s17, 1
	s_nop 0
	v_addc_co_u32_e32 v61, vcc, 0, v61, vcc
	global_load_dwordx4 v[60:63], v[60:61], off nt
	s_waitcnt vmcnt(0)
	ds_write2_b32 v71, v0, v1 offset1:1
	ds_write2_b32 v71, v2, v3 offset0:2 offset1:3
	v_add_u32_e32 v0, 0x410, v71
	ds_write2_b32 v0, v4, v5 offset1:1
	v_add_u32_e32 v0, 0x418, v71
	ds_write2_b32 v0, v6, v7 offset1:1
	v_add_u32_e32 v0, 0x820, v71
	s_add_u32 s18, s15, s7
	s_addc_u32 s19, s34, 0
	v_lshlrev_b32_e32 v128, 1, v66
	ds_write2_b32 v0, v8, v9 offset1:1
	v_add_u32_e32 v0, 0x828, v71
	ds_write2_b32 v0, v10, v11 offset1:1
	v_add_u32_e32 v0, 0xc30, v71
	ds_write2_b32 v0, v12, v13 offset1:1
	v_add_u32_e32 v0, 0xc38, v71
	ds_write2_b32 v0, v14, v15 offset1:1
	v_add_u32_e32 v0, 0x1040, v71
	v_readlane_b32 s20, v254, 15
	v_readlane_b32 s21, v254, 16
	v_readlane_b32 s22, v254, 17
	ds_write2_b32 v0, v16, v17 offset1:1
	v_add_u32_e32 v0, 0x1048, v71
	ds_write2_b32 v0, v18, v19 offset1:1
	v_add_u32_e32 v0, 0x1450, v71
	ds_write2_b32 v0, v20, v21 offset1:1
	v_add_u32_e32 v0, 0x1458, v71
	ds_write2_b32 v0, v22, v23 offset1:1
	v_add_u32_e32 v0, 0x1860, v71
	v_readlane_b32 s23, v254, 18
	v_readlane_b32 s24, v254, 19
	v_readlane_b32 s25, v254, 20
	ds_write2_b32 v0, v24, v25 offset1:1
	v_add_u32_e32 v0, 0x1868, v71
	ds_write2_b32 v0, v26, v27 offset1:1
	v_add_u32_e32 v0, 0x1c70, v71
	ds_write2_b32 v0, v28, v29 offset1:1
	v_add_u32_e32 v0, 0x1c78, v71
	ds_write2_b32 v0, v30, v31 offset1:1
	v_add_u32_e32 v0, 0x2080, v71
	v_readlane_b32 s28, v254, 23
	v_readlane_b32 s29, v254, 24
	v_readlane_b32 s30, v254, 25
	ds_write2_b32 v0, v32, v33 offset1:1
	v_add_u32_e32 v0, 0x2088, v71
	ds_write2_b32 v0, v34, v35 offset1:1
	v_add_u32_e32 v0, 0x2490, v71
	ds_write2_b32 v0, v36, v37 offset1:1
	v_add_u32_e32 v0, 0x2498, v71
	ds_write2_b32 v0, v38, v39 offset1:1
	v_add_u32_e32 v0, 0x28a0, v71
	v_readlane_b32 s31, v254, 26
	ds_write2_b32 v0, v40, v41 offset1:1
	v_add_u32_e32 v0, 0x28a8, v71
	ds_write2_b32 v0, v42, v43 offset1:1
	v_add_u32_e32 v0, 0x2cb0, v71
	ds_write2_b32 v0, v44, v45 offset1:1
	v_add_u32_e32 v0, 0x2cb8, v71
	ds_write2_b32 v0, v46, v47 offset1:1
	v_add_u32_e32 v0, 0x30c0, v71
	ds_write2_b32 v0, v48, v49 offset1:1
	v_add_u32_e32 v0, 0x30c8, v71
	ds_write2_b32 v0, v50, v51 offset1:1
	v_add_u32_e32 v0, 0x34d0, v71
	ds_write2_b32 v0, v52, v53 offset1:1
	v_add_u32_e32 v0, 0x34d8, v71
	ds_write2_b32 v0, v54, v55 offset1:1
	v_add_u32_e32 v0, 0x38e0, v71
	ds_write2_b32 v0, v56, v57 offset1:1
	v_add_u32_e32 v0, 0x38e8, v71
	ds_write2_b32 v0, v58, v59 offset1:1
	v_add_u32_e32 v0, 0x3cf0, v71
	ds_write2_b32 v0, v60, v61 offset1:1
	v_add_u32_e32 v0, 0x3cf8, v71
	ds_write2_b32 v0, v62, v63 offset1:1
	s_waitcnt lgkmcnt(0)
; #define LAS __attribute__((address_space(3)))
; __device__ __forceinline__ unsigned cvtpk(float lo, float hi) { f32x2 v = {lo, hi}; bf16x2_t b = __builtin_convertvector(v, bf16x2_t); return __builtin_bit_cast(unsigned, b); }
; __device__ __forceinline__ void tr_item(const float* W, int K, int N, bf16_t* WT, const float* gain, int perm, LAS float* scr, int item, int lane) {
;     ...
;     const int c = lane & 7;
; #pragma unroll
;     for (int j = 0; j < 8; ++j) { const int n = (lane >> 3) + 8 * j; const LAS float* s = scr + (8 * c) * 65 + n;
;         u32x4 o; o.x = cvtpk(s[0 * 65], s[1 * 65]); o.y = cvtpk(s[2 * 65], s[3 * 65]); o.z = cvtpk(s[4 * 65], s[5 * 65]); o.w = cvtpk(s[6 * 65], s[7 * 65]);
;         const int ncol = n0 + n; int drow = ncol;
;         if (perm) { const int hf = ncol >= DFF ? 1 : 0, jj = ncol - hf * DFF; drow = 256 * (jj >> 7) + 128 * hf + (jj & 127); }
;         *(u32x4*)(WT + (size_t)drow * K + k0 + 8 * c) = o; }
;     asm volatile("s_waitcnt lgkmcnt(0)" ::: "memory");
	ds_read_b32 v2, v73
	ds_read_b32 v3, v73 offset:260
	ds_read_b32 v6, v73 offset:520
	ds_read_b32 v7, v73 offset:780
	ds_read_b32 v8, v73 offset:1040
	ds_read_b32 v9, v73 offset:1300
	ds_read_b32 v10, v73 offset:1560
	ds_read_b32 v11, v73 offset:1820
	v_lshl_add_u64 v[0:1], s[18:19], 0, v[128:129]
	s_mov_b64 s[18:19], 0x2c00000
	v_lshl_add_u64 v[4:5], v[0:1], 0, s[18:19]
	s_waitcnt lgkmcnt(0)
	v_cvt_pk_bf16_f32 v1, v6, v7
	v_or_b32_e32 v6, s6, v72
	v_mul_u32_u24_e32 v6, 0x1600, v6
	v_lshlrev_b32_e32 v128, 1, v6
	v_cvt_pk_bf16_f32 v0, v2, v3
	v_cvt_pk_bf16_f32 v2, v8, v9
	v_cvt_pk_bf16_f32 v3, v10, v11
	v_lshl_add_u64 v[6:7], v[4:5], 0, v[128:129]
	flat_store_dwordx4 v[6:7], v[0:3]
	ds_read_b32 v0, v73 offset:32
	ds_read_b32 v1, v73 offset:292
	ds_read_b32 v2, v73 offset:552
	ds_read_b32 v3, v73 offset:812
	ds_read_b32 v6, v73 offset:1072
	ds_read_b32 v7, v73 offset:1332
	ds_read_b32 v8, v73 offset:1592
	ds_read_b32 v9, v73 offset:1852
	s_waitcnt lgkmcnt(0)
	v_cvt_pk_bf16_f32 v0, v0, v1
	v_cvt_pk_bf16_f32 v1, v2, v3
	v_cvt_pk_bf16_f32 v2, v6, v7
	v_or_b32_e32 v6, s6, v74
	v_mul_u32_u24_e32 v6, 0x1600, v6
	v_lshlrev_b32_e32 v128, 1, v6
	v_cvt_pk_bf16_f32 v3, v8, v9
	v_lshl_add_u64 v[6:7], v[4:5], 0, v[128:129]
	flat_store_dwordx4 v[6:7], v[0:3]
	ds_read_b32 v0, v73 offset:64
	ds_read_b32 v1, v73 offset:324
	ds_read_b32 v2, v73 offset:584
	ds_read_b32 v3, v73 offset:844
	ds_read_b32 v6, v73 offset:1104
	ds_read_b32 v7, v73 offset:1364
	ds_read_b32 v8, v73 offset:1624
	ds_read_b32 v9, v73 offset:1884
	s_waitcnt lgkmcnt(0)
	v_cvt_pk_bf16_f32 v0, v0, v1
	v_cvt_pk_bf16_f32 v1, v2, v3
	v_cvt_pk_bf16_f32 v2, v6, v7
	v_or_b32_e32 v6, s6, v75
	v_mul_u32_u24_e32 v6, 0x1600, v6
	v_lshlrev_b32_e32 v128, 1, v6
	v_cvt_pk_bf16_f32 v3, v8, v9
	v_lshl_add_u64 v[6:7], v[4:5], 0, v[128:129]
	flat_store_dwordx4 v[6:7], v[0:3]
	ds_read_b32 v0, v73 offset:96
	ds_read_b32 v1, v73 offset:356
	ds_read_b32 v2, v73 offset:616
	ds_read_b32 v3, v73 offset:876
	ds_read_b32 v6, v73 offset:1136
	ds_read_b32 v7, v73 offset:1396
	ds_read_b32 v8, v73 offset:1656
	ds_read_b32 v9, v73 offset:1916
	s_waitcnt lgkmcnt(0)
	v_cvt_pk_bf16_f32 v0, v0, v1
	v_cvt_pk_bf16_f32 v1, v2, v3
	v_cvt_pk_bf16_f32 v2, v6, v7
	v_or_b32_e32 v6, s6, v76
	v_mul_u32_u24_e32 v6, 0x1600, v6
	v_lshlrev_b32_e32 v128, 1, v6
	v_cvt_pk_bf16_f32 v3, v8, v9
	v_lshl_add_u64 v[6:7], v[4:5], 0, v[128:129]
	flat_store_dwordx4 v[6:7], v[0:3]
	ds_read_b32 v0, v73 offset:128
	ds_read_b32 v1, v73 offset:388
	ds_read_b32 v2, v73 offset:648
	ds_read_b32 v3, v73 offset:908
	ds_read_b32 v6, v73 offset:1168
	ds_read_b32 v7, v73 offset:1428
	ds_read_b32 v8, v73 offset:1688
	ds_read_b32 v9, v73 offset:1948
	s_waitcnt lgkmcnt(0)
	v_cvt_pk_bf16_f32 v0, v0, v1
	v_cvt_pk_bf16_f32 v1, v2, v3
	v_cvt_pk_bf16_f32 v2, v6, v7
	v_or_b32_e32 v6, s6, v77
	v_mul_u32_u24_e32 v6, 0x1600, v6
	v_lshlrev_b32_e32 v128, 1, v6
	v_cvt_pk_bf16_f32 v3, v8, v9
	v_lshl_add_u64 v[6:7], v[4:5], 0, v[128:129]
	flat_store_dwordx4 v[6:7], v[0:3]
	ds_read_b32 v0, v73 offset:160
	ds_read_b32 v1, v73 offset:420
	ds_read_b32 v2, v73 offset:680
	ds_read_b32 v3, v73 offset:940
	ds_read_b32 v6, v73 offset:1200
	ds_read_b32 v7, v73 offset:1460
	ds_read_b32 v8, v73 offset:1720
	ds_read_b32 v9, v73 offset:1980
	s_waitcnt lgkmcnt(0)
	v_cvt_pk_bf16_f32 v0, v0, v1
	v_cvt_pk_bf16_f32 v1, v2, v3
	v_cvt_pk_bf16_f32 v2, v6, v7
	v_or_b32_e32 v6, s6, v78
	v_mul_u32_u24_e32 v6, 0x1600, v6
	v_lshlrev_b32_e32 v128, 1, v6
	v_cvt_pk_bf16_f32 v3, v8, v9
	v_lshl_add_u64 v[6:7], v[4:5], 0, v[128:129]
	flat_store_dwordx4 v[6:7], v[0:3]
	ds_read_b32 v0, v73 offset:192
	ds_read_b32 v1, v73 offset:452
	ds_read_b32 v2, v73 offset:712
	ds_read_b32 v3, v73 offset:972
	ds_read_b32 v6, v73 offset:1232
	ds_read_b32 v7, v73 offset:1492
	ds_read_b32 v8, v73 offset:1752
	ds_read_b32 v9, v73 offset:2012
	s_waitcnt lgkmcnt(0)
	v_cvt_pk_bf16_f32 v0, v0, v1
	v_cvt_pk_bf16_f32 v1, v2, v3
	v_cvt_pk_bf16_f32 v2, v6, v7
	v_or_b32_e32 v6, s6, v79
	v_mul_u32_u24_e32 v6, 0x1600, v6
	v_lshlrev_b32_e32 v128, 1, v6
	v_cvt_pk_bf16_f32 v3, v8, v9
	v_lshl_add_u64 v[6:7], v[4:5], 0, v[128:129]
	flat_store_dwordx4 v[6:7], v[0:3]
	ds_read_b32 v0, v73 offset:224
	ds_read_b32 v1, v73 offset:484
	ds_read_b32 v2, v73 offset:744
	ds_read_b32 v3, v73 offset:1004
	ds_read_b32 v6, v73 offset:1264
	ds_read_b32 v7, v73 offset:1524
	ds_read_b32 v8, v73 offset:1784
	ds_read_b32 v9, v73 offset:2044
	v_or_b32_e32 v10, s6, v80
	s_waitcnt lgkmcnt(0)
	v_cvt_pk_bf16_f32 v0, v0, v1
	v_cvt_pk_bf16_f32 v1, v2, v3
	v_cvt_pk_bf16_f32 v2, v6, v7
	v_mul_u32_u24_e32 v6, 0x1600, v10
	v_lshlrev_b32_e32 v128, 1, v6
	v_cvt_pk_bf16_f32 v3, v8, v9
	v_lshl_add_u64 v[4:5], v[4:5], 0, v[128:129]
	flat_store_dwordx4 v[4:5], v[0:3]
	s_waitcnt lgkmcnt(0)

; __device__ __forceinline__ void tr_item(const float* W, int K, int N, bf16_t* WT, const float* gain, int perm, LAS float* scr, int item, int lane) {
;     const int nblk = N / 64, kb = item / nblk, nb = item % nblk, k0 = 64 * kb, n0 = 64 * nb, lr = lane >> 4, c4 = lane & 15;
;     f32x4 v[16];
; #pragma unroll
;     for (int i = 0; i < 16; ++i) v[i] = *(const f32x4*)(W + (size_t)(k0 + lr + 4 * i) * N + n0 + 4 * c4);
;     if (gain) {
; #pragma unroll
;         for (int i = 0; i < 16; ++i) v[i] = v[i] * gain[k0 + lr + 4 * i];
;     }
; __global__ void __launch_bounds__(512, 2) mk_fwd(Args a) {
;     ...
;                 if (r < I_GU) { tr_item((const float*)a.in[17] + (size_t)l * DM * 2 * DFF, DM, 2 * DFF, (bf16_t*)((unsigned char*)wl + WT_GU2), (const float*)a.in[16] + l * DM, 1, scr, r, lane); continue; } r -= I_GU;
.LBB0_624:
	s_andn2_b64 vcc, exec, s[6:7]
	s_cbranch_vccnz .LBB0_628
	s_and_b64 s[6:7], s[0:1], exec
	s_cselect_b32 s6, 0x5800000, 0
	s_add_u32 s6, s54, s6
	s_addc_u32 s7, s55, 0
	s_add_i32 s9, s8, 0xea00
	s_and_b32 s17, s9, 0xffff
	s_mul_i32 s17, s17, 0xba2f
	s_lshr_b32 s17, s17, 23
	s_mul_i32 s18, s17, 0xb0
	s_sub_i32 s9, s9, s18
	s_lshl_b32 s19, s9, 8
	s_lshl_b32 s17, s17, 6
	s_lshl_b32 s18, s9, 6
	s_and_b32 s19, s19, 0x3ff00
	s_add_u32 s6, s6, s19
	v_or_b32_e32 v68, s17, v70
	s_addc_u32 s7, s7, 0
	v_lshlrev_b32_e32 v128, 2, v64
	v_lshl_add_u64 v[0:1], s[6:7], 0, v[128:129]
	v_or_b32_e32 v4, 4, v68
	v_mad_u64_u32 v[2:3], s[6:7], v68, s63, v[0:1]
	v_mad_u64_u32 v[4:5], s[6:7], v4, s63, v[0:1]
	global_load_dwordx4 v[60:63], v[2:3], off nt
	global_load_dwordx4 v[48:51], v[4:5], off nt
	v_or_b32_e32 v2, 8, v68
	v_or_b32_e32 v4, 12, v68
	v_mad_u64_u32 v[2:3], s[6:7], v2, s63, v[0:1]
	v_mad_u64_u32 v[4:5], s[6:7], v4, s63, v[0:1]
	global_load_dwordx4 v[56:59], v[2:3], off nt
	global_load_dwordx4 v[40:43], v[4:5], off nt
	v_or_b32_e32 v2, 16, v68
	v_or_b32_e32 v4, 20, v68
	v_mad_u64_u32 v[2:3], s[6:7], v2, s63, v[0:1]
	v_mad_u64_u32 v[4:5], s[6:7], v4, s63, v[0:1]
	global_load_dwordx4 v[52:55], v[2:3], off nt
	global_load_dwordx4 v[32:35], v[4:5], off nt
	v_or_b32_e32 v2, 24, v68
	v_or_b32_e32 v4, 28, v68
	v_mad_u64_u32 v[2:3], s[6:7], v2, s63, v[0:1]
	v_mad_u64_u32 v[4:5], s[6:7], v4, s63, v[0:1]
	global_load_dwordx4 v[44:47], v[2:3], off nt
	global_load_dwordx4 v[24:27], v[4:5], off nt
	v_or_b32_e32 v2, 32, v68
	v_or_b32_e32 v4, 36, v68
	v_mad_u64_u32 v[2:3], s[6:7], v2, s63, v[0:1]
	v_mad_u64_u32 v[4:5], s[6:7], v4, s63, v[0:1]
	global_load_dwordx4 v[36:39], v[2:3], off nt
	global_load_dwordx4 v[16:19], v[4:5], off nt
	v_or_b32_e32 v2, 40, v68
	v_or_b32_e32 v4, 44, v68
	v_mad_u64_u32 v[2:3], s[6:7], v2, s63, v[0:1]
	v_mad_u64_u32 v[4:5], s[6:7], v4, s63, v[0:1]
	global_load_dwordx4 v[28:31], v[2:3], off nt
	global_load_dwordx4 v[8:11], v[4:5], off nt
	v_or_b32_e32 v2, 48, v68
	v_or_b32_e32 v4, 52, v68
	v_mad_u64_u32 v[2:3], s[6:7], v2, s63, v[0:1]
	v_mad_u64_u32 v[4:5], s[6:7], v4, s63, v[0:1]
	global_load_dwordx4 v[20:23], v[2:3], off nt
	s_nop 0
	global_load_dwordx4 v[4:7], v[4:5], off nt
	v_or_b32_e32 v2, 56, v68
	v_or_b32_e32 v12, 60, v68
	v_mad_u64_u32 v[2:3], s[6:7], v2, s63, v[0:1]
	v_mad_u64_u32 v[0:1], s[6:7], v12, s63, v[0:1]
	global_load_dwordx4 v[12:15], v[2:3], off nt
	s_nop 0
	global_load_dwordx4 v[0:3], v[0:1], off nt
	v_readlane_b32 s6, v254, 4
	v_readlane_b32 s7, v254, 5
	s_andn2_b64 vcc, exec, s[6:7]
	s_cbranch_vccnz .LBB0_627
	s_and_b64 s[6:7], s[0:1], exec
	s_cselect_b32 s6, 0x2000, 0
	s_add_u32 s6, s52, s6
	s_addc_u32 s7, s53, 0
	v_lshlrev_b32_e32 v69, 2, v68
	global_load_dword v84, v69, s[6:7]
	global_load_dword v86, v69, s[6:7] offset:16
	global_load_dword v88, v69, s[6:7] offset:32
	global_load_dword v90, v69, s[6:7] offset:48
	global_load_dword v92, v69, s[6:7] offset:64
	global_load_dword v94, v69, s[6:7] offset:80
	global_load_dword v96, v69, s[6:7] offset:96
	global_load_dword v98, v69, s[6:7] offset:112
	global_load_dword v100, v69, s[6:7] offset:128
	global_load_dword v102, v69, s[6:7] offset:144
	global_load_dword v104, v69, s[6:7] offset:160
	global_load_dword v106, v69, s[6:7] offset:176
	global_load_dword v108, v69, s[6:7] offset:192
	global_load_dword v110, v69, s[6:7] offset:208
	global_load_dword v112, v69, s[6:7] offset:224
	global_load_dword v114, v69, s[6:7] offset:240
	s_waitcnt vmcnt(0)
	v_pk_mul_f32 v[62:63], v[62:63], v[84:85] op_sel_hi:[1,0]
	v_pk_mul_f32 v[60:61], v[60:61], v[84:85] op_sel_hi:[1,0]
	v_pk_mul_f32 v[50:51], v[50:51], v[86:87] op_sel_hi:[1,0]
	v_pk_mul_f32 v[48:49], v[48:49], v[86:87] op_sel_hi:[1,0]
	v_pk_mul_f32 v[58:59], v[58:59], v[88:89] op_sel_hi:[1,0]
	v_pk_mul_f32 v[56:57], v[56:57], v[88:89] op_sel_hi:[1,0]
	v_pk_mul_f32 v[42:43], v[42:43], v[90:91] op_sel_hi:[1,0]
	v_pk_mul_f32 v[40:41], v[40:41], v[90:91] op_sel_hi:[1,0]
	v_pk_mul_f32 v[54:55], v[54:55], v[92:93] op_sel_hi:[1,0]
	v_pk_mul_f32 v[52:53], v[52:53], v[92:93] op_sel_hi:[1,0]
	v_pk_mul_f32 v[34:35], v[34:35], v[94:95] op_sel_hi:[1,0]
	v_pk_mul_f32 v[32:33], v[32:33], v[94:95] op_sel_hi:[1,0]
	v_pk_mul_f32 v[46:47], v[46:47], v[96:97] op_sel_hi:[1,0]
	v_pk_mul_f32 v[44:45], v[44:45], v[96:97] op_sel_hi:[1,0]
	v_pk_mul_f32 v[26:27], v[26:27], v[98:99] op_sel_hi:[1,0]
	v_pk_mul_f32 v[24:25], v[24:25], v[98:99] op_sel_hi:[1,0]
	v_pk_mul_f32 v[38:39], v[38:39], v[100:101] op_sel_hi:[1,0]
	v_pk_mul_f32 v[36:37], v[36:37], v[100:101] op_sel_hi:[1,0]
	v_pk_mul_f32 v[18:19], v[18:19], v[102:103] op_sel_hi:[1,0]
	v_pk_mul_f32 v[16:17], v[16:17], v[102:103] op_sel_hi:[1,0]
	v_pk_mul_f32 v[30:31], v[30:31], v[104:105] op_sel_hi:[1,0]
	v_pk_mul_f32 v[28:29], v[28:29], v[104:105] op_sel_hi:[1,0]
	v_pk_mul_f32 v[10:11], v[10:11], v[106:107] op_sel_hi:[1,0]
	v_pk_mul_f32 v[8:9], v[8:9], v[106:107] op_sel_hi:[1,0]
	v_pk_mul_f32 v[22:23], v[22:23], v[108:109] op_sel_hi:[1,0]
	v_pk_mul_f32 v[20:21], v[20:21], v[108:109] op_sel_hi:[1,0]
	v_pk_mul_f32 v[6:7], v[6:7], v[110:111] op_sel_hi:[1,0]
	v_pk_mul_f32 v[4:5], v[4:5], v[110:111] op_sel_hi:[1,0]
	v_pk_mul_f32 v[14:15], v[14:15], v[112:113] op_sel_hi:[1,0]
	v_pk_mul_f32 v[12:13], v[12:13], v[112:113] op_sel_hi:[1,0]
	v_pk_mul_f32 v[2:3], v[2:3], v[114:115] op_sel_hi:[1,0]
	v_pk_mul_f32 v[0:1], v[0:1], v[114:115] op_sel_hi:[1,0]

; __device__ __forceinline__ void tr_item(const float* W, int K, int N, bf16_t* WT, const float* gain, int perm, LAS float* scr, int item, int lane) {
;     const int nblk = N / 64, kb = item / nblk, nb = item % nblk, k0 = 64 * kb, n0 = 64 * nb, lr = lane >> 4, c4 = lane & 15;
;     f32x4 v[16];
; #pragma unroll
;     for (int i = 0; i < 16; ++i) v[i] = *(const f32x4*)(W + (size_t)(k0 + lr + 4 * i) * N + n0 + 4 * c4);
;     if (gain) {
; #pragma unroll
;         for (int i = 0; i < 16; ++i) v[i] = v[i] * gain[k0 + lr + 4 * i];
;     }
; __global__ void __launch_bounds__(512, 2) mk_fwd(Args a) {
;     ...
;                 if (r < I_GU) { tr_item((const float*)a.in[4] + (size_t)l * DM * 2 * DFF, DM, 2 * DFF, (bf16_t*)((unsigned char*)wl + WT_GU1), (const float*)a.in[3] + l * DM, 1, scr, r, lane); continue; } r -= I_GU;
.LBB0_630:
	s_and_b64 s[6:7], s[0:1], exec
	v_readlane_b32 s16, v254, 11
	s_cselect_b32 s6, 0x5800000, 0
	v_readlane_b32 s24, v254, 19
	v_readlane_b32 s17, v254, 12
	v_readlane_b32 s25, v254, 20
	s_add_u32 s9, s24, s6
	s_mul_hi_i32 s6, s8, 0x2e8ba2e9
	s_addc_u32 s17, s25, 0
	s_lshr_b32 s7, s6, 31
	s_ashr_i32 s6, s6, 5
	s_add_i32 s6, s6, s7
	s_mul_i32 s7, s6, 0xb0
	s_sub_i32 s7, s8, s7
	s_lshl_b32 s8, s6, 6
	s_lshl_b32 s6, s7, 6
	v_readlane_b32 s18, v254, 13
	v_readlane_b32 s19, v254, 14
	s_ashr_i32 s7, s6, 31
	s_lshl_b64 s[18:19], s[6:7], 2
	s_add_u32 s18, s9, s18
	v_or_b32_e32 v68, s8, v70
	s_addc_u32 s19, s17, s19
	v_lshlrev_b32_e32 v128, 2, v64
	v_lshl_add_u64 v[0:1], s[18:19], 0, v[128:129]
	v_or_b32_e32 v4, 4, v68
	v_mad_i64_i32 v[2:3], s[18:19], v68, s63, v[0:1]
	v_mad_i64_i32 v[4:5], s[18:19], v4, s63, v[0:1]
	global_load_dwordx4 v[60:63], v[2:3], off nt
	global_load_dwordx4 v[48:51], v[4:5], off nt
	v_or_b32_e32 v2, 8, v68
	v_or_b32_e32 v4, 12, v68
	v_mad_i64_i32 v[2:3], s[18:19], v2, s63, v[0:1]
	v_mad_i64_i32 v[4:5], s[18:19], v4, s63, v[0:1]
	global_load_dwordx4 v[56:59], v[2:3], off nt
	global_load_dwordx4 v[40:43], v[4:5], off nt
	v_or_b32_e32 v2, 16, v68
	v_or_b32_e32 v4, 20, v68
	v_mad_i64_i32 v[2:3], s[18:19], v2, s63, v[0:1]
	v_mad_i64_i32 v[4:5], s[18:19], v4, s63, v[0:1]
	global_load_dwordx4 v[52:55], v[2:3], off nt
	global_load_dwordx4 v[32:35], v[4:5], off nt
	v_or_b32_e32 v2, 24, v68
	v_or_b32_e32 v4, 28, v68
	v_mad_i64_i32 v[2:3], s[18:19], v2, s63, v[0:1]
	v_mad_i64_i32 v[4:5], s[18:19], v4, s63, v[0:1]
	global_load_dwordx4 v[44:47], v[2:3], off nt
	global_load_dwordx4 v[24:27], v[4:5], off nt
	v_or_b32_e32 v2, 32, v68
	v_or_b32_e32 v4, 36, v68
	v_mad_i64_i32 v[2:3], s[18:19], v2, s63, v[0:1]
	v_mad_i64_i32 v[4:5], s[18:19], v4, s63, v[0:1]
	global_load_dwordx4 v[36:39], v[2:3], off nt
	global_load_dwordx4 v[16:19], v[4:5], off nt
	v_or_b32_e32 v2, 40, v68
	v_or_b32_e32 v4, 44, v68
	v_mad_i64_i32 v[2:3], s[18:19], v2, s63, v[0:1]
	v_mad_i64_i32 v[4:5], s[18:19], v4, s63, v[0:1]
	global_load_dwordx4 v[28:31], v[2:3], off nt
	global_load_dwordx4 v[8:11], v[4:5], off nt
	v_or_b32_e32 v2, 48, v68
	v_or_b32_e32 v4, 52, v68
	v_mad_i64_i32 v[2:3], s[18:19], v2, s63, v[0:1]
	v_mad_i64_i32 v[4:5], s[18:19], v4, s63, v[0:1]
	global_load_dwordx4 v[20:23], v[2:3], off nt
	s_nop 0
	global_load_dwordx4 v[4:7], v[4:5], off nt
	v_or_b32_e32 v2, 56, v68
	v_or_b32_e32 v12, 60, v68
	v_mad_i64_i32 v[2:3], s[18:19], v2, s63, v[0:1]
	v_mad_i64_i32 v[0:1], s[18:19], v12, s63, v[0:1]
	global_load_dwordx4 v[12:15], v[2:3], off nt
	s_nop 0
	global_load_dwordx4 v[0:3], v[0:1], off nt
	v_readlane_b32 s16, v254, 6
	v_readlane_b32 s17, v254, 7
	v_readlane_b32 s22, v254, 17
	v_readlane_b32 s23, v254, 18
	s_andn2_b64 vcc, exec, s[16:17]
	v_readlane_b32 s20, v254, 15
	v_readlane_b32 s21, v254, 16
	v_readlane_b32 s26, v254, 21
	v_readlane_b32 s27, v254, 22
	v_readlane_b32 s28, v254, 23
	v_readlane_b32 s29, v254, 24
	v_readlane_b32 s30, v254, 25
	v_readlane_b32 s31, v254, 26
	s_cbranch_vccnz .LBB0_605
	s_and_b64 s[0:1], s[0:1], exec
	s_cselect_b32 s0, 0x2000, 0
	s_add_u32 s0, s22, s0
	v_ashrrev_i32_e32 v69, 31, v68
	s_addc_u32 s1, s23, 0
	v_lshl_add_u64 v[68:69], v[68:69], 2, s[0:1]
	global_load_dword v84, v[68:69], off
	global_load_dword v86, v[68:69], off offset:16
	global_load_dword v88, v[68:69], off offset:32
	global_load_dword v90, v[68:69], off offset:48
	global_load_dword v92, v[68:69], off offset:64
	global_load_dword v94, v[68:69], off offset:80
	global_load_dword v96, v[68:69], off offset:96
	global_load_dword v98, v[68:69], off offset:112
	global_load_dword v100, v[68:69], off offset:128
	global_load_dword v102, v[68:69], off offset:144
	global_load_dword v104, v[68:69], off offset:160
	global_load_dword v106, v[68:69], off offset:176
	global_load_dword v108, v[68:69], off offset:192
	global_load_dword v110, v[68:69], off offset:208
	global_load_dword v112, v[68:69], off offset:224
	global_load_dword v114, v[68:69], off offset:240
	s_waitcnt vmcnt(0)
	v_pk_mul_f32 v[62:63], v[62:63], v[84:85] op_sel_hi:[1,0]
	v_pk_mul_f32 v[60:61], v[60:61], v[84:85] op_sel_hi:[1,0]
	v_pk_mul_f32 v[50:51], v[50:51], v[86:87] op_sel_hi:[1,0]
	v_pk_mul_f32 v[48:49], v[48:49], v[86:87] op_sel_hi:[1,0]
	v_pk_mul_f32 v[58:59], v[58:59], v[88:89] op_sel_hi:[1,0]
	v_pk_mul_f32 v[56:57], v[56:57], v[88:89] op_sel_hi:[1,0]
	v_pk_mul_f32 v[42:43], v[42:43], v[90:91] op_sel_hi:[1,0]
	v_pk_mul_f32 v[40:41], v[40:41], v[90:91] op_sel_hi:[1,0]
	v_pk_mul_f32 v[54:55], v[54:55], v[92:93] op_sel_hi:[1,0]
	v_pk_mul_f32 v[52:53], v[52:53], v[92:93] op_sel_hi:[1,0]
	v_pk_mul_f32 v[34:35], v[34:35], v[94:95] op_sel_hi:[1,0]
	v_pk_mul_f32 v[32:33], v[32:33], v[94:95] op_sel_hi:[1,0]
	v_pk_mul_f32 v[46:47], v[46:47], v[96:97] op_sel_hi:[1,0]
	v_pk_mul_f32 v[44:45], v[44:45], v[96:97] op_sel_hi:[1,0]
	v_pk_mul_f32 v[26:27], v[26:27], v[98:99] op_sel_hi:[1,0]
	v_pk_mul_f32 v[24:25], v[24:25], v[98:99] op_sel_hi:[1,0]
	v_pk_mul_f32 v[38:39], v[38:39], v[100:101] op_sel_hi:[1,0]
	v_pk_mul_f32 v[36:37], v[36:37], v[100:101] op_sel_hi:[1,0]
	v_pk_mul_f32 v[18:19], v[18:19], v[102:103] op_sel_hi:[1,0]
	v_pk_mul_f32 v[16:17], v[16:17], v[102:103] op_sel_hi:[1,0]
	v_pk_mul_f32 v[30:31], v[30:31], v[104:105] op_sel_hi:[1,0]
	v_pk_mul_f32 v[28:29], v[28:29], v[104:105] op_sel_hi:[1,0]
	v_pk_mul_f32 v[10:11], v[10:11], v[106:107] op_sel_hi:[1,0]
	v_pk_mul_f32 v[8:9], v[8:9], v[106:107] op_sel_hi:[1,0]
	v_pk_mul_f32 v[22:23], v[22:23], v[108:109] op_sel_hi:[1,0]
	v_pk_mul_f32 v[20:21], v[20:21], v[108:109] op_sel_hi:[1,0]
	v_pk_mul_f32 v[6:7], v[6:7], v[110:111] op_sel_hi:[1,0]
	v_pk_mul_f32 v[4:5], v[4:5], v[110:111] op_sel_hi:[1,0]
	v_pk_mul_f32 v[14:15], v[14:15], v[112:113] op_sel_hi:[1,0]
	v_pk_mul_f32 v[12:13], v[12:13], v[112:113] op_sel_hi:[1,0]
	v_pk_mul_f32 v[2:3], v[2:3], v[114:115] op_sel_hi:[1,0]
	v_pk_mul_f32 v[0:1], v[0:1], v[114:115] op_sel_hi:[1,0]
	s_branch .LBB0_605

; __device__ __forceinline__ unsigned cvtpk(float lo, float hi) { f32x2 v = {lo, hi}; bf16x2_t b = __builtin_convertvector(v, bf16x2_t); return __builtin_bit_cast(unsigned, b); }
; __global__ void __launch_bounds__(512, 2) mk_fwd(Args a) {
;     ...
;             for (int row = gw; row < SEQ; row += NGW) {
;                 const f32x4* xr = (const f32x4*)(x_in + (size_t)row * DM) + lane;
;                 f32x4 v[8]; float ss = 0.f;
; #pragma unroll
;                 for (int j = 0; j < 8; ++j) { v[j] = xr[64 * j]; ss += (v[j][0] * v[j][0] + v[j][1] * v[j][1]) + (v[j][2] * v[j][2] + v[j][3] * v[j][3]); }
;                 ss = wave_sum(ss);
;                 u32x2* o = (u32x2*)(XB + (size_t)row * DM) + lane;
; #pragma unroll
;                 for (int j = 0; j < 8; ++j) o[64 * j] = (u32x2){cvtpk(v[j][0], v[j][1]), cvtpk(v[j][2], v[j][3])};
;                 if (lane < 32) SSQ[(size_t)row * 32 + lane] = lane == 0 ? ss : 0.f;
;             }
.LBB0_638:
	v_add_co_u32_e32 v4, vcc, 0xfffff000, v36
	global_load_dwordx4 v[20:23], v[36:37], off offset:-3072 nt
	s_nop 0
	v_addc_co_u32_e32 v5, vcc, -1, v37, vcc
	global_load_dwordx4 v[28:31], v[4:5], off offset:-3072 nt
	s_mov_b32 s5, 0x15e00000
	global_load_dwordx4 v[24:27], v[36:37], off offset:-2048 nt
	s_waitcnt vmcnt(0)
	v_mul_f32_e32 v0, v29, v29
	v_mul_f32_e32 v1, v31, v31
	v_fmac_f32_e32 v0, v28, v28
	v_fmac_f32_e32 v1, v30, v30
	v_add_f32_e32 v6, v0, v1
	global_load_dwordx4 v[0:3], v[4:5], off offset:-2048 nt
	v_cvt_pk_bf16_f32 v28, v28, v29
	v_cvt_pk_bf16_f32 v29, v30, v31
	s_waitcnt vmcnt(0)
	v_mul_f32_e32 v7, v1, v1
	v_mul_f32_e32 v8, v3, v3
	v_fmac_f32_e32 v7, v0, v0
	v_fmac_f32_e32 v8, v2, v2
	v_add_f32_e32 v7, v7, v8
	v_add_f32_e32 v8, v6, v7
	global_load_dwordx4 v[4:7], v[4:5], off offset:-1024 nt
	v_cvt_pk_bf16_f32 v0, v0, v1
	v_cvt_pk_bf16_f32 v1, v2, v3
	s_waitcnt vmcnt(0)
	v_mul_f32_e32 v9, v5, v5
	v_mul_f32_e32 v10, v7, v7
	v_fmac_f32_e32 v9, v4, v4
	v_fmac_f32_e32 v10, v6, v6
	v_add_f32_e32 v9, v9, v10
	v_add_f32_e32 v12, v8, v9
	global_load_dwordx4 v[8:11], v[36:37], off offset:-4096 nt
	s_waitcnt vmcnt(0)
	v_mul_f32_e32 v13, v9, v9
	v_mul_f32_e32 v14, v11, v11
	v_fmac_f32_e32 v13, v8, v8
	v_fmac_f32_e32 v14, v10, v10
	v_add_f32_e32 v13, v13, v14
	v_add_f32_e32 v12, v12, v13
	v_mul_f32_e32 v13, v21, v21
	v_mul_f32_e32 v14, v23, v23
	v_fmac_f32_e32 v13, v20, v20
	v_fmac_f32_e32 v14, v22, v22
	v_add_f32_e32 v13, v13, v14
	v_add_f32_e32 v12, v12, v13
	v_mul_f32_e32 v13, v25, v25
	v_mul_f32_e32 v14, v27, v27
	v_fmac_f32_e32 v13, v24, v24
	v_fmac_f32_e32 v14, v26, v26
	v_add_f32_e32 v13, v13, v14
	v_add_f32_e32 v16, v12, v13
	global_load_dwordx4 v[12:15], v[36:37], off offset:-1024 nt
	s_waitcnt vmcnt(0)
	v_mul_f32_e32 v17, v13, v13
	v_mul_f32_e32 v18, v15, v15
	v_fmac_f32_e32 v17, v12, v12
	v_fmac_f32_e32 v18, v14, v14
	v_add_f32_e32 v17, v17, v18
	v_add_f32_e32 v44, v16, v17
	global_load_dwordx4 v[16:19], v[36:37], off nt
	s_waitcnt vmcnt(0) lgkmcnt(0)
	v_mul_f32_e32 v45, v17, v17
	v_mul_f32_e32 v46, v19, v19
	v_fmac_f32_e32 v45, v16, v16
	v_fmac_f32_e32 v46, v18, v18
	v_add_f32_e32 v45, v45, v46
	v_add_f32_e32 v44, v44, v45
	ds_bpermute_b32 v45, v38, v44
	v_lshl_add_u64 v[46:47], s[80:81], 0, v[34:35]
	v_add_co_u32_e32 v30, vcc, s5, v46
	s_waitcnt lgkmcnt(0)
	v_add_f32_e32 v44, v44, v45
	ds_bpermute_b32 v45, v39, v44
	v_addc_co_u32_e32 v31, vcc, 0, v47, vcc
	flat_store_dwordx2 v[30:31], v[0:1] offset:512
	v_cvt_pk_bf16_f32 v0, v4, v5
	s_waitcnt lgkmcnt(0)
	v_add_f32_e32 v44, v44, v45
	ds_bpermute_b32 v45, v40, v44
	v_cvt_pk_bf16_f32 v1, v6, v7
	flat_store_dwordx2 v[30:31], v[0:1] offset:1024
	v_cvt_pk_bf16_f32 v0, v8, v9
	v_cvt_pk_bf16_f32 v1, v10, v11
	s_waitcnt lgkmcnt(0)
	v_add_f32_e32 v44, v44, v45
	ds_bpermute_b32 v45, v41, v44
	flat_store_dwordx2 v[30:31], v[0:1] offset:1536
	v_cvt_pk_bf16_f32 v0, v20, v21
	v_cvt_pk_bf16_f32 v1, v22, v23
	flat_store_dwordx2 v[30:31], v[0:1] offset:2048
	s_waitcnt lgkmcnt(0)
	v_add_f32_e32 v44, v44, v45
	ds_bpermute_b32 v45, v42, v44
	v_cvt_pk_bf16_f32 v0, v24, v25
	v_cvt_pk_bf16_f32 v1, v26, v27
	flat_store_dwordx2 v[30:31], v[0:1] offset:2560
	v_cvt_pk_bf16_f32 v0, v12, v13
	s_waitcnt lgkmcnt(0)
	v_add_f32_e32 v44, v44, v45
	ds_bpermute_b32 v45, v43, v44
	v_cvt_pk_bf16_f32 v1, v14, v15
	flat_store_dwordx2 v[30:31], v[0:1] offset:3072
	v_cvt_pk_bf16_f32 v0, v16, v17
	v_cvt_pk_bf16_f32 v1, v18, v19
	flat_store_dwordx2 v[30:31], v[28:29]
	flat_store_dwordx2 v[30:31], v[0:1] offset:3584
	s_and_saveexec_b64 s[30:31], s[6:7]
	s_cbranch_execz .LBB0_637
	s_waitcnt lgkmcnt(0)
	v_add_f32_e32 v2, v44, v45
	v_lshl_add_u64 v[0:1], s[80:81], 0, v[32:33]
	v_cndmask_b32_e64 v2, 0, v2, s[8:9]
	flat_store_dword v[0:1], v2
	s_branch .LBB0_637
